# P3 EpiMix: gate loads of the mid hook (2 groups ahead) and of the epilogue (14 ahead) issued early into free fragment registers, counted vmcnt instead of 32 serialized round trips
# speedup vs baseline: 1.0133x; 1.0031x over previous
; #define MIXR(a_, b_) ((1.0f + __builtin_amdgcn_exp2f(-(b_) * LOG2E)) * __builtin_amdgcn_rcpf(1.0f + __builtin_amdgcn_exp2f(-(a_) * LOG2E)))
;     __device__ __forceinline__ void mid(f32x4 (&acc)[2][2][4][2], const Unit& u, int wr, int wc, int fr, int fq) const {
;         int row0 = u.pm * BM + wr * 64 + fr, col0 = u.pn * BM + wc * 32 + fq * 8;
;         asm volatile("" : "+v"(row0), "+v"(col0));
; #pragma unroll
;         for (int ai = 0; ai < 2; ++ai)
; #pragma unroll
;             for (int m = 0; m < 4; ++m) {
;                 const int row = row0 + ai * HALF + m * 16;
; #pragma unroll
;                 for (int bj = 0; bj < 2; ++bj) {
;                     const int col = col0 + bj * HALF;
;                     const u32x4 za = *(const u32x4*)(Z + (size_t)row * NZ + ZGA + col), zb = *(const u32x4*)(Z + (size_t)row * NZ + ZGB + col);
;     ...
;                     acc[ai][bj][m][0][0] *= MIXR(bflo(za.x), bflo(zb.x)); acc[ai][bj][m][0][1] *= MIXR(bfhi(za.x), bfhi(zb.x));
;                     acc[ai][bj][m][0][2] *= MIXR(bflo(za.y), bflo(zb.y)); acc[ai][bj][m][0][3] *= MIXR(bfhi(za.y), bfhi(zb.y));
;                     acc[ai][bj][m][1][0] *= MIXR(bflo(za.z), bflo(zb.z)); acc[ai][bj][m][1][1] *= MIXR(bfhi(za.z), bfhi(zb.z));
;                     acc[ai][bj][m][1][2] *= MIXR(bflo(za.w), bflo(zb.w)); acc[ai][bj][m][1][3] *= MIXR(bfhi(za.w), bfhi(zb.w));
;     ...
;                     asm volatile("" ::: "memory"); __builtin_amdgcn_sched_barrier(0);
;                 }
.LBB0_927:
	s_cmpk_lg_i32 s6, 0x200
	s_cbranch_scc1 .LBB0_926
	v_mov_b32_e32 v1, v156
	v_mov_b32_e32 v132, v158
	v_mov_b64_e32 v[2:3], s[2:3]
	v_ashrrev_i32_e32 v133, 31, v132
	v_mad_i64_i32 v[134:135], s[8:9], v1, s16, v[2:3]
	v_lshlrev_b64 v[164:165], 1, v[132:133]
	v_lshl_add_u64 v[136:137], v[134:135], 0, v[164:165]
	v_add_co_u32_e32 v138, vcc, 0x3000, v136
	v_lshl_add_u64 v[166:167], v[136:137], 0, s[48:49]
	s_nop 0
	v_addc_co_u32_e32 v139, vcc, 0, v137, vcc
	v_mul_lo_u32 v0, v156, s16
	v_lshl_add_u32 v0, v158, 1, v0
	v_add_u32_e32 v0, 0x3200, v0
	global_load_dwordx4 v[180:183], v0, s[2:3]
	global_load_dwordx4 v[184:187], v0, s[2:3] offset:2048
	global_load_dwordx4 v[188:191], v0, s[2:3] offset:256
	global_load_dwordx4 v[192:195], v0, s[2:3] offset:2304
	v_add_u32_e32 v159, 0x42000, v0
	global_load_dwordx4 v[196:199], v159, s[2:3]
	global_load_dwordx4 v[200:203], v159, s[2:3] offset:2048
	global_load_dwordx4 v[204:207], v159, s[2:3] offset:256
	global_load_dwordx4 v[208:211], v159, s[2:3] offset:2304
	v_lshl_add_u64 v[168:169], v[136:137], 0, s[46:47]
	v_add_u32_e32 v159, 0x84000, v0
	global_load_dwordx4 v[212:215], v159, s[2:3]
	global_load_dwordx4 v[216:219], v159, s[2:3] offset:2048
	global_load_dwordx4 v[220:223], v159, s[2:3] offset:256
	global_load_dwordx4 v[224:227], v159, s[2:3] offset:2304
	s_waitcnt vmcnt(8)
	v_lshlrev_b32_e32 v157, 16, v184
	v_mul_f32_e32 v157, 0xbfb8aa3b, v157
	v_exp_f32_e32 v176, v157
	v_lshlrev_b32_e32 v157, 16, v180
	v_and_b32_e32 v180, 0xffff0000, v180
	v_mul_f32_e32 v180, 0xbfb8aa3b, v180
	v_exp_f32_e32 v180, v180
	v_and_b32_e32 v184, 0xffff0000, v184
	v_mul_f32_e32 v184, 0xbfb8aa3b, v184
	v_exp_f32_e32 v177, v184
	v_add_f32_e32 v180, 1.0, v180
	v_rcp_f32_e32 v179, v180
	v_lshlrev_b32_e32 v180, 16, v185
	v_mul_f32_e32 v180, 0xbfb8aa3b, v180
	v_exp_f32_e32 v184, v180
	v_lshlrev_b32_e32 v180, 16, v181
	v_and_b32_e32 v181, 0xffff0000, v181
	v_mul_f32_e32 v180, 0xbfb8aa3b, v180
	v_mul_f32_e32 v181, 0xbfb8aa3b, v181
	v_exp_f32_e32 v180, v180
	v_exp_f32_e32 v181, v181
	v_and_b32_e32 v185, 0xffff0000, v185
	v_mul_f32_e32 v185, 0xbfb8aa3b, v185
	v_add_f32_e32 v180, 1.0, v180
	v_exp_f32_e32 v185, v185
	v_add_f32_e32 v181, 1.0, v181
	v_rcp_f32_e32 v180, v180
	v_rcp_f32_e32 v181, v181
	v_pk_add_f32 v[184:185], v[184:185], 1.0 op_sel_hi:[1,0]
	v_mul_f32_e32 v157, 0xbfb8aa3b, v157
	v_exp_f32_e32 v157, v157
	v_pk_mul_f32 v[180:181], v[184:185], v[180:181]
	v_pk_add_f32 v[176:177], v[176:177], 1.0 op_sel_hi:[1,0]
	v_pk_mul_f32 v[130:131], v[130:131], v[180:181]
	v_lshlrev_b32_e32 v180, 16, v186
	v_and_b32_e32 v181, 0xffff0000, v186
	v_mul_f32_e32 v180, 0xbfb8aa3b, v180
	v_mul_f32_e32 v181, 0xbfb8aa3b, v181
	v_exp_f32_e32 v184, v180
	v_lshlrev_b32_e32 v180, 16, v182
	v_exp_f32_e32 v185, v181
	v_and_b32_e32 v181, 0xffff0000, v182
	v_lshlrev_b32_e32 v182, 16, v187
	v_mul_f32_e32 v182, 0xbfb8aa3b, v182
	v_exp_f32_e32 v186, v182
	v_lshlrev_b32_e32 v182, 16, v183
	v_and_b32_e32 v183, 0xffff0000, v183
	v_mul_f32_e32 v180, 0xbfb8aa3b, v180
	v_mul_f32_e32 v181, 0xbfb8aa3b, v181
	v_mul_f32_e32 v182, 0xbfb8aa3b, v182
	v_mul_f32_e32 v183, 0xbfb8aa3b, v183
	v_exp_f32_e32 v180, v180
	v_exp_f32_e32 v181, v181
	v_exp_f32_e32 v182, v182
	v_exp_f32_e32 v183, v183
	v_and_b32_e32 v187, 0xffff0000, v187
	v_mul_f32_e32 v187, 0xbfb8aa3b, v187
	v_add_f32_e32 v157, 1.0, v157
	v_add_f32_e32 v180, 1.0, v180
	v_add_f32_e32 v181, 1.0, v181
	v_add_f32_e32 v182, 1.0, v182
	v_exp_f32_e32 v187, v187
	v_add_f32_e32 v183, 1.0, v183
	v_rcp_f32_e32 v178, v157
	v_rcp_f32_e32 v180, v180
	v_rcp_f32_e32 v181, v181
	v_rcp_f32_e32 v182, v182
	v_rcp_f32_e32 v183, v183
	v_pk_add_f32 v[186:187], v[186:187], 1.0 op_sel_hi:[1,0]
	v_pk_add_f32 v[184:185], v[184:185], 1.0 op_sel_hi:[1,0]
	v_pk_mul_f32 v[176:177], v[176:177], v[178:179]
	v_pk_mul_f32 v[180:181], v[184:185], v[180:181]
	v_pk_mul_f32 v[182:183], v[186:187], v[182:183]
	v_pk_mul_f32 v[128:129], v[128:129], v[176:177]
	v_pk_mul_f32 v[126:127], v[126:127], v[182:183]
	v_pk_mul_f32 v[124:125], v[124:125], v[180:181]
	v_lshlrev_b32_e32 v157, 16, v192
	v_mul_f32_e32 v157, 0xbfb8aa3b, v157
	v_exp_f32_e32 v166, v157
	v_lshlrev_b32_e32 v157, 16, v188
	v_and_b32_e32 v188, 0xffff0000, v188
	v_mul_f32_e32 v188, 0xbfb8aa3b, v188
	v_exp_f32_e32 v188, v188
	v_and_b32_e32 v192, 0xffff0000, v192
	v_mul_f32_e32 v192, 0xbfb8aa3b, v192
	v_exp_f32_e32 v167, v192
	v_add_f32_e32 v188, 1.0, v188
	v_rcp_f32_e32 v169, v188
	v_lshlrev_b32_e32 v188, 16, v193
	v_mul_f32_e32 v188, 0xbfb8aa3b, v188
	v_exp_f32_e32 v192, v188
	v_lshlrev_b32_e32 v188, 16, v189
	v_and_b32_e32 v189, 0xffff0000, v189
	v_mul_f32_e32 v188, 0xbfb8aa3b, v188
	v_mul_f32_e32 v189, 0xbfb8aa3b, v189
	v_exp_f32_e32 v188, v188
	v_exp_f32_e32 v189, v189
	v_and_b32_e32 v193, 0xffff0000, v193
	v_mul_f32_e32 v193, 0xbfb8aa3b, v193
	v_add_f32_e32 v188, 1.0, v188
	v_exp_f32_e32 v193, v193
	v_add_f32_e32 v189, 1.0, v189
	v_rcp_f32_e32 v188, v188
	v_rcp_f32_e32 v189, v189
	v_pk_add_f32 v[192:193], v[192:193], 1.0 op_sel_hi:[1,0]
	v_mul_f32_e32 v157, 0xbfb8aa3b, v157
	v_exp_f32_e32 v157, v157
	v_pk_mul_f32 v[188:189], v[192:193], v[188:189]
	v_pk_add_f32 v[166:167], v[166:167], 1.0 op_sel_hi:[1,0]
	v_pk_mul_f32 v[122:123], v[122:123], v[188:189]
	v_lshlrev_b32_e32 v188, 16, v194
	v_and_b32_e32 v189, 0xffff0000, v194
	v_mul_f32_e32 v188, 0xbfb8aa3b, v188
	v_mul_f32_e32 v189, 0xbfb8aa3b, v189
	v_exp_f32_e32 v192, v188
	v_lshlrev_b32_e32 v188, 16, v190
	v_exp_f32_e32 v193, v189
	v_and_b32_e32 v189, 0xffff0000, v190
	v_lshlrev_b32_e32 v190, 16, v195
	v_mul_f32_e32 v190, 0xbfb8aa3b, v190
	v_exp_f32_e32 v194, v190
	v_lshlrev_b32_e32 v190, 16, v191
	v_and_b32_e32 v191, 0xffff0000, v191
; #define MIXR(a_, b_) ((1.0f + __builtin_amdgcn_exp2f(-(b_) * LOG2E)) * __builtin_amdgcn_rcpf(1.0f + __builtin_amdgcn_exp2f(-(a_) * LOG2E)))
;     __device__ __forceinline__ void mid(f32x4 (&acc)[2][2][4][2], const Unit& u, int wr, int wc, int fr, int fq) const {
;         int row0 = u.pm * BM + wr * 64 + fr, col0 = u.pn * BM + wc * 32 + fq * 8;
;         asm volatile("" : "+v"(row0), "+v"(col0));
; #pragma unroll
;         for (int ai = 0; ai < 2; ++ai)
; #pragma unroll
;             for (int m = 0; m < 4; ++m) {
;                 const int row = row0 + ai * HALF + m * 16;
; #pragma unroll
;                 for (int bj = 0; bj < 2; ++bj) {
;                     const int col = col0 + bj * HALF;
;                     const u32x4 za = *(const u32x4*)(Z + (size_t)row * NZ + ZGA + col), zb = *(const u32x4*)(Z + (size_t)row * NZ + ZGB + col);
;     ...
;                     acc[ai][bj][m][0][0] *= MIXR(bflo(za.x), bflo(zb.x)); acc[ai][bj][m][0][1] *= MIXR(bfhi(za.x), bfhi(zb.x));
;                     acc[ai][bj][m][0][2] *= MIXR(bflo(za.y), bflo(zb.y)); acc[ai][bj][m][0][3] *= MIXR(bfhi(za.y), bfhi(zb.y));
;                     acc[ai][bj][m][1][0] *= MIXR(bflo(za.z), bflo(zb.z)); acc[ai][bj][m][1][1] *= MIXR(bfhi(za.z), bfhi(zb.z));
;                     acc[ai][bj][m][1][2] *= MIXR(bflo(za.w), bflo(zb.w)); acc[ai][bj][m][1][3] *= MIXR(bfhi(za.w), bfhi(zb.w));
;     ...
;                     asm volatile("" ::: "memory"); __builtin_amdgcn_sched_barrier(0);
;                 }
	v_mul_f32_e32 v188, 0xbfb8aa3b, v188
	v_mul_f32_e32 v189, 0xbfb8aa3b, v189
	v_mul_f32_e32 v190, 0xbfb8aa3b, v190
	v_mul_f32_e32 v191, 0xbfb8aa3b, v191
	v_exp_f32_e32 v188, v188
	v_exp_f32_e32 v189, v189
	v_exp_f32_e32 v190, v190
	v_exp_f32_e32 v191, v191
	v_and_b32_e32 v195, 0xffff0000, v195
	v_mul_f32_e32 v195, 0xbfb8aa3b, v195
	v_add_f32_e32 v157, 1.0, v157
	v_add_f32_e32 v188, 1.0, v188
	v_add_f32_e32 v189, 1.0, v189
	v_add_f32_e32 v190, 1.0, v190
	v_exp_f32_e32 v195, v195
	v_add_f32_e32 v191, 1.0, v191
	v_rcp_f32_e32 v168, v157
	v_rcp_f32_e32 v188, v188
	v_rcp_f32_e32 v189, v189
	v_rcp_f32_e32 v190, v190
	v_rcp_f32_e32 v191, v191
	v_pk_add_f32 v[194:195], v[194:195], 1.0 op_sel_hi:[1,0]
	v_pk_add_f32 v[192:193], v[192:193], 1.0 op_sel_hi:[1,0]
	v_pk_mul_f32 v[166:167], v[166:167], v[168:169]
	v_pk_mul_f32 v[188:189], v[192:193], v[188:189]
	v_pk_mul_f32 v[190:191], v[194:195], v[190:191]
	v_pk_mul_f32 v[120:121], v[120:121], v[166:167]
	v_pk_mul_f32 v[118:119], v[118:119], v[190:191]
	v_pk_mul_f32 v[116:117], v[116:117], v[188:189]
	v_add_u32_e32 v132, 16, v1
	v_mad_i64_i32 v[132:133], s[8:9], v132, s16, v[2:3]
	v_lshl_add_u64 v[136:137], v[132:133], 0, v[164:165]
	v_add_co_u32_e32 v138, vcc, s17, v136
	v_lshl_add_u64 v[166:167], v[136:137], 0, s[48:49]
	s_nop 0
	v_addc_co_u32_e32 v139, vcc, 0, v137, vcc
	v_lshl_add_u64 v[168:169], v[136:137], 0, s[46:47]
	v_add_u32_e32 v159, 0xc6000, v0
	global_load_dwordx4 v[180:183], v159, s[2:3]
	global_load_dwordx4 v[184:187], v159, s[2:3] offset:2048
	global_load_dwordx4 v[188:191], v159, s[2:3] offset:256
	global_load_dwordx4 v[192:195], v159, s[2:3] offset:2304
	s_waitcnt vmcnt(8)
	v_lshlrev_b32_e32 v157, 16, v200
	v_mul_f32_e32 v157, 0xbfb8aa3b, v157
	v_exp_f32_e32 v176, v157
	v_lshlrev_b32_e32 v157, 16, v196
	v_and_b32_e32 v196, 0xffff0000, v196
	v_mul_f32_e32 v196, 0xbfb8aa3b, v196
	v_exp_f32_e32 v196, v196
	v_and_b32_e32 v200, 0xffff0000, v200
	v_mul_f32_e32 v200, 0xbfb8aa3b, v200
	v_exp_f32_e32 v177, v200
	v_add_f32_e32 v196, 1.0, v196
	v_rcp_f32_e32 v179, v196
	v_lshlrev_b32_e32 v196, 16, v201
	v_mul_f32_e32 v196, 0xbfb8aa3b, v196
	v_exp_f32_e32 v200, v196
	v_lshlrev_b32_e32 v196, 16, v197
	v_and_b32_e32 v197, 0xffff0000, v197
	v_mul_f32_e32 v196, 0xbfb8aa3b, v196
	v_mul_f32_e32 v197, 0xbfb8aa3b, v197
	v_exp_f32_e32 v196, v196
	v_exp_f32_e32 v197, v197
	v_and_b32_e32 v201, 0xffff0000, v201
	v_mul_f32_e32 v201, 0xbfb8aa3b, v201
	v_add_f32_e32 v196, 1.0, v196
	v_exp_f32_e32 v201, v201
	v_add_f32_e32 v197, 1.0, v197
	v_rcp_f32_e32 v196, v196
	v_rcp_f32_e32 v197, v197
	v_pk_add_f32 v[200:201], v[200:201], 1.0 op_sel_hi:[1,0]
	v_mul_f32_e32 v157, 0xbfb8aa3b, v157
	v_exp_f32_e32 v157, v157
	v_pk_mul_f32 v[196:197], v[200:201], v[196:197]
	v_pk_add_f32 v[176:177], v[176:177], 1.0 op_sel_hi:[1,0]
	v_pk_mul_f32 v[114:115], v[114:115], v[196:197]
	v_lshlrev_b32_e32 v196, 16, v202
	v_and_b32_e32 v197, 0xffff0000, v202
	v_mul_f32_e32 v196, 0xbfb8aa3b, v196
	v_mul_f32_e32 v197, 0xbfb8aa3b, v197
	v_exp_f32_e32 v200, v196
	v_lshlrev_b32_e32 v196, 16, v198
	v_exp_f32_e32 v201, v197
	v_and_b32_e32 v197, 0xffff0000, v198
	v_lshlrev_b32_e32 v198, 16, v203
	v_mul_f32_e32 v198, 0xbfb8aa3b, v198
	v_exp_f32_e32 v202, v198
	v_lshlrev_b32_e32 v198, 16, v199
	v_and_b32_e32 v199, 0xffff0000, v199
	v_mul_f32_e32 v196, 0xbfb8aa3b, v196
	v_mul_f32_e32 v197, 0xbfb8aa3b, v197
	v_mul_f32_e32 v198, 0xbfb8aa3b, v198
	v_mul_f32_e32 v199, 0xbfb8aa3b, v199
	v_exp_f32_e32 v196, v196
	v_exp_f32_e32 v197, v197
	v_exp_f32_e32 v198, v198
	v_exp_f32_e32 v199, v199
	v_and_b32_e32 v203, 0xffff0000, v203
	v_mul_f32_e32 v203, 0xbfb8aa3b, v203
	v_add_f32_e32 v157, 1.0, v157
	v_add_f32_e32 v196, 1.0, v196
	v_add_f32_e32 v197, 1.0, v197
	v_add_f32_e32 v198, 1.0, v198
	v_exp_f32_e32 v203, v203
	v_add_f32_e32 v199, 1.0, v199
	v_rcp_f32_e32 v178, v157
	v_rcp_f32_e32 v196, v196
	v_rcp_f32_e32 v197, v197
	v_rcp_f32_e32 v198, v198
	v_rcp_f32_e32 v199, v199
	v_pk_add_f32 v[202:203], v[202:203], 1.0 op_sel_hi:[1,0]
	v_pk_add_f32 v[200:201], v[200:201], 1.0 op_sel_hi:[1,0]
	v_pk_mul_f32 v[176:177], v[176:177], v[178:179]
	v_pk_mul_f32 v[196:197], v[200:201], v[196:197]
	v_pk_mul_f32 v[198:199], v[202:203], v[198:199]
	v_pk_mul_f32 v[112:113], v[112:113], v[176:177]
	v_pk_mul_f32 v[110:111], v[110:111], v[198:199]
	v_pk_mul_f32 v[108:109], v[108:109], v[196:197]
	v_lshlrev_b32_e32 v157, 16, v208
	v_mul_f32_e32 v157, 0xbfb8aa3b, v157
	v_exp_f32_e32 v166, v157
	v_lshlrev_b32_e32 v157, 16, v204
	v_and_b32_e32 v204, 0xffff0000, v204
	v_mul_f32_e32 v204, 0xbfb8aa3b, v204
	v_exp_f32_e32 v204, v204
	v_and_b32_e32 v208, 0xffff0000, v208
	v_mul_f32_e32 v208, 0xbfb8aa3b, v208
	v_exp_f32_e32 v167, v208
	v_add_f32_e32 v204, 1.0, v204
	v_rcp_f32_e32 v169, v204
	v_lshlrev_b32_e32 v204, 16, v209
	v_mul_f32_e32 v204, 0xbfb8aa3b, v204
	v_exp_f32_e32 v208, v204
	v_lshlrev_b32_e32 v204, 16, v205
	v_and_b32_e32 v205, 0xffff0000, v205
	v_mul_f32_e32 v204, 0xbfb8aa3b, v204
	v_mul_f32_e32 v205, 0xbfb8aa3b, v205
	v_exp_f32_e32 v204, v204
	v_exp_f32_e32 v205, v205
	v_and_b32_e32 v209, 0xffff0000, v209
	v_mul_f32_e32 v209, 0xbfb8aa3b, v209
	v_add_f32_e32 v204, 1.0, v204
	v_exp_f32_e32 v209, v209
	v_add_f32_e32 v205, 1.0, v205
	v_rcp_f32_e32 v204, v204
	v_rcp_f32_e32 v205, v205
	v_pk_add_f32 v[208:209], v[208:209], 1.0 op_sel_hi:[1,0]
	v_mul_f32_e32 v157, 0xbfb8aa3b, v157
	v_exp_f32_e32 v157, v157
	v_pk_mul_f32 v[204:205], v[208:209], v[204:205]
	v_pk_add_f32 v[166:167], v[166:167], 1.0 op_sel_hi:[1,0]
	v_pk_mul_f32 v[106:107], v[106:107], v[204:205]
	v_lshlrev_b32_e32 v204, 16, v210
	v_and_b32_e32 v205, 0xffff0000, v210
	v_mul_f32_e32 v204, 0xbfb8aa3b, v204
; #define MIXR(a_, b_) ((1.0f + __builtin_amdgcn_exp2f(-(b_) * LOG2E)) * __builtin_amdgcn_rcpf(1.0f + __builtin_amdgcn_exp2f(-(a_) * LOG2E)))
;     __device__ __forceinline__ void mid(f32x4 (&acc)[2][2][4][2], const Unit& u, int wr, int wc, int fr, int fq) const {
;         int row0 = u.pm * BM + wr * 64 + fr, col0 = u.pn * BM + wc * 32 + fq * 8;
;         asm volatile("" : "+v"(row0), "+v"(col0));
; #pragma unroll
;         for (int ai = 0; ai < 2; ++ai)
; #pragma unroll
;             for (int m = 0; m < 4; ++m) {
;                 const int row = row0 + ai * HALF + m * 16;
; #pragma unroll
;                 for (int bj = 0; bj < 2; ++bj) {
;                     const int col = col0 + bj * HALF;
;                     const u32x4 za = *(const u32x4*)(Z + (size_t)row * NZ + ZGA + col), zb = *(const u32x4*)(Z + (size_t)row * NZ + ZGB + col);
;     ...
;                     acc[ai][bj][m][0][0] *= MIXR(bflo(za.x), bflo(zb.x)); acc[ai][bj][m][0][1] *= MIXR(bfhi(za.x), bfhi(zb.x));
;                     acc[ai][bj][m][0][2] *= MIXR(bflo(za.y), bflo(zb.y)); acc[ai][bj][m][0][3] *= MIXR(bfhi(za.y), bfhi(zb.y));
;                     acc[ai][bj][m][1][0] *= MIXR(bflo(za.z), bflo(zb.z)); acc[ai][bj][m][1][1] *= MIXR(bfhi(za.z), bfhi(zb.z));
;                     acc[ai][bj][m][1][2] *= MIXR(bflo(za.w), bflo(zb.w)); acc[ai][bj][m][1][3] *= MIXR(bfhi(za.w), bfhi(zb.w));
;     ...
;                     asm volatile("" ::: "memory"); __builtin_amdgcn_sched_barrier(0);
;                 }
	v_mul_f32_e32 v205, 0xbfb8aa3b, v205
	v_exp_f32_e32 v208, v204
	v_lshlrev_b32_e32 v204, 16, v206
	v_exp_f32_e32 v209, v205
	v_and_b32_e32 v205, 0xffff0000, v206
	v_lshlrev_b32_e32 v206, 16, v211
	v_mul_f32_e32 v206, 0xbfb8aa3b, v206
	v_exp_f32_e32 v210, v206
	v_lshlrev_b32_e32 v206, 16, v207
	v_and_b32_e32 v207, 0xffff0000, v207
	v_mul_f32_e32 v204, 0xbfb8aa3b, v204
	v_mul_f32_e32 v205, 0xbfb8aa3b, v205
	v_mul_f32_e32 v206, 0xbfb8aa3b, v206
	v_mul_f32_e32 v207, 0xbfb8aa3b, v207
	v_exp_f32_e32 v204, v204
	v_exp_f32_e32 v205, v205
	v_exp_f32_e32 v206, v206
	v_exp_f32_e32 v207, v207
	v_and_b32_e32 v211, 0xffff0000, v211
	v_mul_f32_e32 v211, 0xbfb8aa3b, v211
	v_add_f32_e32 v157, 1.0, v157
	v_add_f32_e32 v204, 1.0, v204
	v_add_f32_e32 v205, 1.0, v205
	v_add_f32_e32 v206, 1.0, v206
	v_exp_f32_e32 v211, v211
	v_add_f32_e32 v207, 1.0, v207
	v_rcp_f32_e32 v168, v157
	v_rcp_f32_e32 v204, v204
	v_rcp_f32_e32 v205, v205
	v_rcp_f32_e32 v206, v206
	v_rcp_f32_e32 v207, v207
	v_pk_add_f32 v[210:211], v[210:211], 1.0 op_sel_hi:[1,0]
	v_pk_add_f32 v[208:209], v[208:209], 1.0 op_sel_hi:[1,0]
	v_pk_mul_f32 v[166:167], v[166:167], v[168:169]
	v_pk_mul_f32 v[204:205], v[208:209], v[204:205]
	v_pk_mul_f32 v[206:207], v[210:211], v[206:207]
	v_pk_mul_f32 v[104:105], v[104:105], v[166:167]
	v_pk_mul_f32 v[102:103], v[102:103], v[206:207]
	v_pk_mul_f32 v[100:101], v[100:101], v[204:205]
	v_add_u32_e32 v132, 32, v1
	v_mad_i64_i32 v[132:133], s[8:9], v132, s16, v[2:3]
	v_lshl_add_u64 v[136:137], v[132:133], 0, v[164:165]
	v_add_co_u32_e32 v138, vcc, s17, v136
	v_lshl_add_u64 v[166:167], v[136:137], 0, s[48:49]
	s_nop 0
	v_addc_co_u32_e32 v139, vcc, 0, v137, vcc
	v_lshl_add_u64 v[168:169], v[136:137], 0, s[46:47]
	v_add_u32_e32 v159, 0x210000, v0
	global_load_dwordx4 v[196:199], v159, s[2:3]
	global_load_dwordx4 v[200:203], v159, s[2:3] offset:2048
	global_load_dwordx4 v[204:207], v159, s[2:3] offset:256
	global_load_dwordx4 v[208:211], v159, s[2:3] offset:2304
	s_waitcnt vmcnt(8)
	v_lshlrev_b32_e32 v157, 16, v216
	v_mul_f32_e32 v157, 0xbfb8aa3b, v157
	v_exp_f32_e32 v176, v157
	v_lshlrev_b32_e32 v157, 16, v212
	v_and_b32_e32 v212, 0xffff0000, v212
	v_mul_f32_e32 v212, 0xbfb8aa3b, v212
	v_exp_f32_e32 v212, v212
	v_and_b32_e32 v216, 0xffff0000, v216
	v_mul_f32_e32 v216, 0xbfb8aa3b, v216
	v_exp_f32_e32 v177, v216
	v_add_f32_e32 v212, 1.0, v212
	v_rcp_f32_e32 v179, v212
	v_lshlrev_b32_e32 v212, 16, v217
	v_mul_f32_e32 v212, 0xbfb8aa3b, v212
	v_exp_f32_e32 v216, v212
	v_lshlrev_b32_e32 v212, 16, v213
	v_and_b32_e32 v213, 0xffff0000, v213
	v_mul_f32_e32 v212, 0xbfb8aa3b, v212
	v_mul_f32_e32 v213, 0xbfb8aa3b, v213
	v_exp_f32_e32 v212, v212
	v_exp_f32_e32 v213, v213
	v_and_b32_e32 v217, 0xffff0000, v217
	v_mul_f32_e32 v217, 0xbfb8aa3b, v217
	v_add_f32_e32 v212, 1.0, v212
	v_exp_f32_e32 v217, v217
	v_add_f32_e32 v213, 1.0, v213
	v_rcp_f32_e32 v212, v212
	v_rcp_f32_e32 v213, v213
	v_pk_add_f32 v[216:217], v[216:217], 1.0 op_sel_hi:[1,0]
	v_mul_f32_e32 v157, 0xbfb8aa3b, v157
	v_exp_f32_e32 v157, v157
	v_pk_mul_f32 v[212:213], v[216:217], v[212:213]
	v_pk_add_f32 v[176:177], v[176:177], 1.0 op_sel_hi:[1,0]
	v_pk_mul_f32 v[98:99], v[98:99], v[212:213]
	v_lshlrev_b32_e32 v212, 16, v218
	v_and_b32_e32 v213, 0xffff0000, v218
	v_mul_f32_e32 v212, 0xbfb8aa3b, v212
	v_mul_f32_e32 v213, 0xbfb8aa3b, v213
	v_exp_f32_e32 v216, v212
	v_lshlrev_b32_e32 v212, 16, v214
	v_exp_f32_e32 v217, v213
	v_and_b32_e32 v213, 0xffff0000, v214
	v_lshlrev_b32_e32 v214, 16, v219
	v_mul_f32_e32 v214, 0xbfb8aa3b, v214
	v_exp_f32_e32 v218, v214
	v_lshlrev_b32_e32 v214, 16, v215
	v_and_b32_e32 v215, 0xffff0000, v215
	v_mul_f32_e32 v212, 0xbfb8aa3b, v212
	v_mul_f32_e32 v213, 0xbfb8aa3b, v213
	v_mul_f32_e32 v214, 0xbfb8aa3b, v214
	v_mul_f32_e32 v215, 0xbfb8aa3b, v215
	v_exp_f32_e32 v212, v212
	v_exp_f32_e32 v213, v213
	v_exp_f32_e32 v214, v214
	v_exp_f32_e32 v215, v215
	v_and_b32_e32 v219, 0xffff0000, v219
	v_mul_f32_e32 v219, 0xbfb8aa3b, v219
	v_add_f32_e32 v157, 1.0, v157
	v_add_f32_e32 v212, 1.0, v212
	v_add_f32_e32 v213, 1.0, v213
	v_add_f32_e32 v214, 1.0, v214
	v_exp_f32_e32 v219, v219
	v_add_f32_e32 v215, 1.0, v215
	v_rcp_f32_e32 v178, v157
	v_rcp_f32_e32 v212, v212
	v_rcp_f32_e32 v213, v213
	v_rcp_f32_e32 v214, v214
	v_rcp_f32_e32 v215, v215
	v_pk_add_f32 v[218:219], v[218:219], 1.0 op_sel_hi:[1,0]
	v_pk_add_f32 v[216:217], v[216:217], 1.0 op_sel_hi:[1,0]
	v_pk_mul_f32 v[176:177], v[176:177], v[178:179]
	v_pk_mul_f32 v[212:213], v[216:217], v[212:213]
	v_pk_mul_f32 v[214:215], v[218:219], v[214:215]
	v_pk_mul_f32 v[96:97], v[96:97], v[176:177]
	v_pk_mul_f32 v[94:95], v[94:95], v[214:215]
	v_pk_mul_f32 v[92:93], v[92:93], v[212:213]
	v_lshlrev_b32_e32 v157, 16, v224
	v_mul_f32_e32 v157, 0xbfb8aa3b, v157
	v_exp_f32_e32 v166, v157
	v_lshlrev_b32_e32 v157, 16, v220
	v_and_b32_e32 v220, 0xffff0000, v220
	v_mul_f32_e32 v220, 0xbfb8aa3b, v220
	v_exp_f32_e32 v220, v220
	v_and_b32_e32 v224, 0xffff0000, v224
	v_mul_f32_e32 v224, 0xbfb8aa3b, v224
	v_exp_f32_e32 v167, v224
	v_add_f32_e32 v220, 1.0, v220
	v_rcp_f32_e32 v169, v220
	v_lshlrev_b32_e32 v220, 16, v225
	v_mul_f32_e32 v220, 0xbfb8aa3b, v220
	v_exp_f32_e32 v224, v220
	v_lshlrev_b32_e32 v220, 16, v221
	v_and_b32_e32 v221, 0xffff0000, v221
	v_mul_f32_e32 v220, 0xbfb8aa3b, v220
	v_mul_f32_e32 v221, 0xbfb8aa3b, v221
	v_exp_f32_e32 v220, v220
	v_exp_f32_e32 v221, v221
	v_and_b32_e32 v225, 0xffff0000, v225
	v_mul_f32_e32 v225, 0xbfb8aa3b, v225
	v_add_f32_e32 v220, 1.0, v220
	v_exp_f32_e32 v225, v225
	v_add_f32_e32 v221, 1.0, v221
	v_rcp_f32_e32 v220, v220
	v_rcp_f32_e32 v221, v221
	v_pk_add_f32 v[224:225], v[224:225], 1.0 op_sel_hi:[1,0]
	v_mul_f32_e32 v157, 0xbfb8aa3b, v157
; #define MIXR(a_, b_) ((1.0f + __builtin_amdgcn_exp2f(-(b_) * LOG2E)) * __builtin_amdgcn_rcpf(1.0f + __builtin_amdgcn_exp2f(-(a_) * LOG2E)))
;     __device__ __forceinline__ void mid(f32x4 (&acc)[2][2][4][2], const Unit& u, int wr, int wc, int fr, int fq) const {
;         int row0 = u.pm * BM + wr * 64 + fr, col0 = u.pn * BM + wc * 32 + fq * 8;
;         asm volatile("" : "+v"(row0), "+v"(col0));
; #pragma unroll
;         for (int ai = 0; ai < 2; ++ai)
; #pragma unroll
;             for (int m = 0; m < 4; ++m) {
;                 const int row = row0 + ai * HALF + m * 16;
; #pragma unroll
;                 for (int bj = 0; bj < 2; ++bj) {
;                     const int col = col0 + bj * HALF;
;                     const u32x4 za = *(const u32x4*)(Z + (size_t)row * NZ + ZGA + col), zb = *(const u32x4*)(Z + (size_t)row * NZ + ZGB + col);
;     ...
;                     acc[ai][bj][m][0][0] *= MIXR(bflo(za.x), bflo(zb.x)); acc[ai][bj][m][0][1] *= MIXR(bfhi(za.x), bfhi(zb.x));
;                     acc[ai][bj][m][0][2] *= MIXR(bflo(za.y), bflo(zb.y)); acc[ai][bj][m][0][3] *= MIXR(bfhi(za.y), bfhi(zb.y));
;                     acc[ai][bj][m][1][0] *= MIXR(bflo(za.z), bflo(zb.z)); acc[ai][bj][m][1][1] *= MIXR(bfhi(za.z), bfhi(zb.z));
;                     acc[ai][bj][m][1][2] *= MIXR(bflo(za.w), bflo(zb.w)); acc[ai][bj][m][1][3] *= MIXR(bfhi(za.w), bfhi(zb.w));
;     ...
;                     asm volatile("" ::: "memory"); __builtin_amdgcn_sched_barrier(0);
;                 }
	v_exp_f32_e32 v157, v157
	v_pk_mul_f32 v[220:221], v[224:225], v[220:221]
	v_pk_add_f32 v[166:167], v[166:167], 1.0 op_sel_hi:[1,0]
	v_pk_mul_f32 v[90:91], v[90:91], v[220:221]
	v_lshlrev_b32_e32 v220, 16, v226
	v_and_b32_e32 v221, 0xffff0000, v226
	v_mul_f32_e32 v220, 0xbfb8aa3b, v220
	v_mul_f32_e32 v221, 0xbfb8aa3b, v221
	v_exp_f32_e32 v224, v220
	v_lshlrev_b32_e32 v220, 16, v222
	v_exp_f32_e32 v225, v221
	v_and_b32_e32 v221, 0xffff0000, v222
	v_lshlrev_b32_e32 v222, 16, v227
	v_mul_f32_e32 v222, 0xbfb8aa3b, v222
	v_exp_f32_e32 v226, v222
	v_lshlrev_b32_e32 v222, 16, v223
	v_and_b32_e32 v223, 0xffff0000, v223
	v_mul_f32_e32 v220, 0xbfb8aa3b, v220
	v_mul_f32_e32 v221, 0xbfb8aa3b, v221
	v_mul_f32_e32 v222, 0xbfb8aa3b, v222
	v_mul_f32_e32 v223, 0xbfb8aa3b, v223
	v_exp_f32_e32 v220, v220
	v_exp_f32_e32 v221, v221
	v_exp_f32_e32 v222, v222
	v_exp_f32_e32 v223, v223
	v_and_b32_e32 v227, 0xffff0000, v227
	v_mul_f32_e32 v227, 0xbfb8aa3b, v227
	v_add_f32_e32 v157, 1.0, v157
	v_add_f32_e32 v220, 1.0, v220
	v_add_f32_e32 v221, 1.0, v221
	v_add_f32_e32 v222, 1.0, v222
	v_exp_f32_e32 v227, v227
	v_add_f32_e32 v223, 1.0, v223
	v_rcp_f32_e32 v168, v157
	v_rcp_f32_e32 v220, v220
	v_rcp_f32_e32 v221, v221
	v_rcp_f32_e32 v222, v222
	v_rcp_f32_e32 v223, v223
	v_pk_add_f32 v[226:227], v[226:227], 1.0 op_sel_hi:[1,0]
	v_pk_add_f32 v[224:225], v[224:225], 1.0 op_sel_hi:[1,0]
	v_pk_mul_f32 v[166:167], v[166:167], v[168:169]
	v_pk_mul_f32 v[220:221], v[224:225], v[220:221]
	v_pk_mul_f32 v[222:223], v[226:227], v[222:223]
	v_pk_mul_f32 v[88:89], v[88:89], v[166:167]
	v_pk_mul_f32 v[86:87], v[86:87], v[222:223]
	v_pk_mul_f32 v[84:85], v[84:85], v[220:221]
	v_add_u32_e32 v132, 48, v1
	v_mad_i64_i32 v[132:133], s[8:9], v132, s16, v[2:3]
	v_lshl_add_u64 v[136:137], v[132:133], 0, v[164:165]
	v_add_co_u32_e32 v138, vcc, s17, v136
	v_lshl_add_u64 v[166:167], v[136:137], 0, s[48:49]
	s_nop 0
	v_addc_co_u32_e32 v139, vcc, 0, v137, vcc
	v_lshl_add_u64 v[168:169], v[136:137], 0, s[46:47]
	v_add_u32_e32 v159, 0x252000, v0
	global_load_dwordx4 v[212:215], v159, s[2:3]
	global_load_dwordx4 v[216:219], v159, s[2:3] offset:2048
	global_load_dwordx4 v[220:223], v159, s[2:3] offset:256
	global_load_dwordx4 v[224:227], v159, s[2:3] offset:2304
	s_waitcnt vmcnt(8)
	v_lshlrev_b32_e32 v157, 16, v184
	v_mul_f32_e32 v157, 0xbfb8aa3b, v157
	v_exp_f32_e32 v176, v157
	v_lshlrev_b32_e32 v157, 16, v180
	v_and_b32_e32 v180, 0xffff0000, v180
	v_mul_f32_e32 v180, 0xbfb8aa3b, v180
	v_exp_f32_e32 v180, v180
	v_and_b32_e32 v184, 0xffff0000, v184
	v_mul_f32_e32 v184, 0xbfb8aa3b, v184
	v_exp_f32_e32 v177, v184
	v_add_f32_e32 v180, 1.0, v180
	v_rcp_f32_e32 v179, v180
	v_lshlrev_b32_e32 v180, 16, v185
	v_mul_f32_e32 v180, 0xbfb8aa3b, v180
	v_exp_f32_e32 v184, v180
	v_lshlrev_b32_e32 v180, 16, v181
	v_and_b32_e32 v181, 0xffff0000, v181
	v_mul_f32_e32 v180, 0xbfb8aa3b, v180
	v_mul_f32_e32 v181, 0xbfb8aa3b, v181
	v_exp_f32_e32 v180, v180
	v_exp_f32_e32 v181, v181
	v_and_b32_e32 v185, 0xffff0000, v185
	v_mul_f32_e32 v185, 0xbfb8aa3b, v185
	v_add_f32_e32 v180, 1.0, v180
	v_exp_f32_e32 v185, v185
	v_add_f32_e32 v181, 1.0, v181
	v_rcp_f32_e32 v180, v180
	v_rcp_f32_e32 v181, v181
	v_pk_add_f32 v[184:185], v[184:185], 1.0 op_sel_hi:[1,0]
	v_mul_f32_e32 v157, 0xbfb8aa3b, v157
	v_exp_f32_e32 v157, v157
	v_pk_mul_f32 v[180:181], v[184:185], v[180:181]
	v_pk_add_f32 v[176:177], v[176:177], 1.0 op_sel_hi:[1,0]
	v_pk_mul_f32 v[82:83], v[82:83], v[180:181]
	v_lshlrev_b32_e32 v180, 16, v186
	v_and_b32_e32 v181, 0xffff0000, v186
	v_mul_f32_e32 v180, 0xbfb8aa3b, v180
	v_mul_f32_e32 v181, 0xbfb8aa3b, v181
	v_exp_f32_e32 v184, v180
	v_lshlrev_b32_e32 v180, 16, v182
	v_exp_f32_e32 v185, v181
	v_and_b32_e32 v181, 0xffff0000, v182
	v_lshlrev_b32_e32 v182, 16, v187
	v_mul_f32_e32 v182, 0xbfb8aa3b, v182
	v_exp_f32_e32 v186, v182
	v_lshlrev_b32_e32 v182, 16, v183
	v_and_b32_e32 v183, 0xffff0000, v183
	v_mul_f32_e32 v180, 0xbfb8aa3b, v180
	v_mul_f32_e32 v181, 0xbfb8aa3b, v181
	v_mul_f32_e32 v182, 0xbfb8aa3b, v182
	v_mul_f32_e32 v183, 0xbfb8aa3b, v183
	v_exp_f32_e32 v180, v180
	v_exp_f32_e32 v181, v181
	v_exp_f32_e32 v182, v182
	v_exp_f32_e32 v183, v183
	v_and_b32_e32 v187, 0xffff0000, v187
	v_mul_f32_e32 v187, 0xbfb8aa3b, v187
	v_add_f32_e32 v157, 1.0, v157
	v_add_f32_e32 v180, 1.0, v180
	v_add_f32_e32 v181, 1.0, v181
	v_add_f32_e32 v182, 1.0, v182
	v_exp_f32_e32 v187, v187
	v_add_f32_e32 v183, 1.0, v183
	v_rcp_f32_e32 v178, v157
	v_rcp_f32_e32 v180, v180
	v_rcp_f32_e32 v181, v181
	v_rcp_f32_e32 v182, v182
	v_rcp_f32_e32 v183, v183
	v_pk_add_f32 v[186:187], v[186:187], 1.0 op_sel_hi:[1,0]
	v_pk_add_f32 v[184:185], v[184:185], 1.0 op_sel_hi:[1,0]
	v_pk_mul_f32 v[176:177], v[176:177], v[178:179]
	v_pk_mul_f32 v[180:181], v[184:185], v[180:181]
	v_pk_mul_f32 v[182:183], v[186:187], v[182:183]
	v_pk_mul_f32 v[80:81], v[80:81], v[176:177]
	v_pk_mul_f32 v[78:79], v[78:79], v[182:183]
	v_pk_mul_f32 v[76:77], v[76:77], v[180:181]
	v_lshlrev_b32_e32 v157, 16, v192
	v_mul_f32_e32 v157, 0xbfb8aa3b, v157
	v_exp_f32_e32 v166, v157
	v_lshlrev_b32_e32 v157, 16, v188
	v_and_b32_e32 v188, 0xffff0000, v188
	v_mul_f32_e32 v188, 0xbfb8aa3b, v188
	v_exp_f32_e32 v188, v188
	v_and_b32_e32 v192, 0xffff0000, v192
	v_mul_f32_e32 v192, 0xbfb8aa3b, v192
	v_exp_f32_e32 v167, v192
	v_add_f32_e32 v188, 1.0, v188
	v_rcp_f32_e32 v169, v188
	v_lshlrev_b32_e32 v188, 16, v193
	v_mul_f32_e32 v188, 0xbfb8aa3b, v188
	v_exp_f32_e32 v192, v188
	v_lshlrev_b32_e32 v188, 16, v189
	v_and_b32_e32 v189, 0xffff0000, v189
	v_mul_f32_e32 v188, 0xbfb8aa3b, v188
	v_mul_f32_e32 v189, 0xbfb8aa3b, v189
	v_exp_f32_e32 v188, v188
	v_exp_f32_e32 v189, v189
	v_and_b32_e32 v193, 0xffff0000, v193
; #define MIXR(a_, b_) ((1.0f + __builtin_amdgcn_exp2f(-(b_) * LOG2E)) * __builtin_amdgcn_rcpf(1.0f + __builtin_amdgcn_exp2f(-(a_) * LOG2E)))
;     __device__ __forceinline__ void mid(f32x4 (&acc)[2][2][4][2], const Unit& u, int wr, int wc, int fr, int fq) const {
;         int row0 = u.pm * BM + wr * 64 + fr, col0 = u.pn * BM + wc * 32 + fq * 8;
;         asm volatile("" : "+v"(row0), "+v"(col0));
; #pragma unroll
;         for (int ai = 0; ai < 2; ++ai)
; #pragma unroll
;             for (int m = 0; m < 4; ++m) {
;                 const int row = row0 + ai * HALF + m * 16;
; #pragma unroll
;                 for (int bj = 0; bj < 2; ++bj) {
;                     const int col = col0 + bj * HALF;
;                     const u32x4 za = *(const u32x4*)(Z + (size_t)row * NZ + ZGA + col), zb = *(const u32x4*)(Z + (size_t)row * NZ + ZGB + col);
;     ...
;                     acc[ai][bj][m][0][0] *= MIXR(bflo(za.x), bflo(zb.x)); acc[ai][bj][m][0][1] *= MIXR(bfhi(za.x), bfhi(zb.x));
;                     acc[ai][bj][m][0][2] *= MIXR(bflo(za.y), bflo(zb.y)); acc[ai][bj][m][0][3] *= MIXR(bfhi(za.y), bfhi(zb.y));
;                     acc[ai][bj][m][1][0] *= MIXR(bflo(za.z), bflo(zb.z)); acc[ai][bj][m][1][1] *= MIXR(bfhi(za.z), bfhi(zb.z));
;                     acc[ai][bj][m][1][2] *= MIXR(bflo(za.w), bflo(zb.w)); acc[ai][bj][m][1][3] *= MIXR(bfhi(za.w), bfhi(zb.w));
;     ...
;                     asm volatile("" ::: "memory"); __builtin_amdgcn_sched_barrier(0);
;                 }
	v_mul_f32_e32 v193, 0xbfb8aa3b, v193
	v_add_f32_e32 v188, 1.0, v188
	v_exp_f32_e32 v193, v193
	v_add_f32_e32 v189, 1.0, v189
	v_rcp_f32_e32 v188, v188
	v_rcp_f32_e32 v189, v189
	v_pk_add_f32 v[192:193], v[192:193], 1.0 op_sel_hi:[1,0]
	v_mul_f32_e32 v157, 0xbfb8aa3b, v157
	v_exp_f32_e32 v157, v157
	v_pk_mul_f32 v[188:189], v[192:193], v[188:189]
	v_pk_add_f32 v[166:167], v[166:167], 1.0 op_sel_hi:[1,0]
	v_pk_mul_f32 v[74:75], v[74:75], v[188:189]
	v_lshlrev_b32_e32 v188, 16, v194
	v_and_b32_e32 v189, 0xffff0000, v194
	v_mul_f32_e32 v188, 0xbfb8aa3b, v188
	v_mul_f32_e32 v189, 0xbfb8aa3b, v189
	v_exp_f32_e32 v192, v188
	v_lshlrev_b32_e32 v188, 16, v190
	v_exp_f32_e32 v193, v189
	v_and_b32_e32 v189, 0xffff0000, v190
	v_lshlrev_b32_e32 v190, 16, v195
	v_mul_f32_e32 v190, 0xbfb8aa3b, v190
	v_exp_f32_e32 v194, v190
	v_lshlrev_b32_e32 v190, 16, v191
	v_and_b32_e32 v191, 0xffff0000, v191
	v_mul_f32_e32 v188, 0xbfb8aa3b, v188
	v_mul_f32_e32 v189, 0xbfb8aa3b, v189
	v_mul_f32_e32 v190, 0xbfb8aa3b, v190
	v_mul_f32_e32 v191, 0xbfb8aa3b, v191
	v_exp_f32_e32 v188, v188
	v_exp_f32_e32 v189, v189
	v_exp_f32_e32 v190, v190
	v_exp_f32_e32 v191, v191
	v_and_b32_e32 v195, 0xffff0000, v195
	v_mul_f32_e32 v195, 0xbfb8aa3b, v195
	v_add_f32_e32 v157, 1.0, v157
	v_add_f32_e32 v188, 1.0, v188
	v_add_f32_e32 v189, 1.0, v189
	v_add_f32_e32 v190, 1.0, v190
	v_exp_f32_e32 v195, v195
	v_add_f32_e32 v191, 1.0, v191
	v_rcp_f32_e32 v168, v157
	v_rcp_f32_e32 v188, v188
	v_rcp_f32_e32 v189, v189
	v_rcp_f32_e32 v190, v190
	v_rcp_f32_e32 v191, v191
	v_pk_add_f32 v[194:195], v[194:195], 1.0 op_sel_hi:[1,0]
	v_pk_add_f32 v[192:193], v[192:193], 1.0 op_sel_hi:[1,0]
	v_pk_mul_f32 v[166:167], v[166:167], v[168:169]
	v_pk_mul_f32 v[188:189], v[192:193], v[188:189]
	v_pk_mul_f32 v[190:191], v[194:195], v[190:191]
	v_pk_mul_f32 v[72:73], v[72:73], v[166:167]
	v_pk_mul_f32 v[70:71], v[70:71], v[190:191]
	v_pk_mul_f32 v[68:69], v[68:69], v[188:189]
	v_add_u32_e32 v132, 0x80, v1
	v_mad_i64_i32 v[132:133], s[8:9], v132, s16, v[2:3]
	v_lshl_add_u64 v[136:137], v[132:133], 0, v[164:165]
	v_add_co_u32_e32 v138, vcc, s17, v136
	v_lshl_add_u64 v[166:167], v[136:137], 0, s[48:49]
	s_nop 0
	v_addc_co_u32_e32 v139, vcc, 0, v137, vcc
	v_lshl_add_u64 v[168:169], v[136:137], 0, s[46:47]
	v_add_u32_e32 v159, 0x294000, v0
	global_load_dwordx4 v[180:183], v159, s[2:3]
	global_load_dwordx4 v[184:187], v159, s[2:3] offset:2048
	global_load_dwordx4 v[188:191], v159, s[2:3] offset:256
	global_load_dwordx4 v[192:195], v159, s[2:3] offset:2304
	s_waitcnt vmcnt(8)
	v_lshlrev_b32_e32 v157, 16, v200
	v_mul_f32_e32 v157, 0xbfb8aa3b, v157
	v_exp_f32_e32 v176, v157
	v_lshlrev_b32_e32 v157, 16, v196
	v_and_b32_e32 v196, 0xffff0000, v196
	v_mul_f32_e32 v196, 0xbfb8aa3b, v196
	v_exp_f32_e32 v196, v196
	v_and_b32_e32 v200, 0xffff0000, v200
	v_mul_f32_e32 v200, 0xbfb8aa3b, v200
	v_exp_f32_e32 v177, v200
	v_add_f32_e32 v196, 1.0, v196
	v_rcp_f32_e32 v179, v196
	v_lshlrev_b32_e32 v196, 16, v201
	v_mul_f32_e32 v196, 0xbfb8aa3b, v196
	v_exp_f32_e32 v200, v196
	v_lshlrev_b32_e32 v196, 16, v197
	v_and_b32_e32 v197, 0xffff0000, v197
	v_mul_f32_e32 v196, 0xbfb8aa3b, v196
	v_mul_f32_e32 v197, 0xbfb8aa3b, v197
	v_exp_f32_e32 v196, v196
	v_exp_f32_e32 v197, v197
	v_and_b32_e32 v201, 0xffff0000, v201
	v_mul_f32_e32 v201, 0xbfb8aa3b, v201
	v_add_f32_e32 v196, 1.0, v196
	v_exp_f32_e32 v201, v201
	v_add_f32_e32 v197, 1.0, v197
	v_rcp_f32_e32 v196, v196
	v_rcp_f32_e32 v197, v197
	v_pk_add_f32 v[200:201], v[200:201], 1.0 op_sel_hi:[1,0]
	v_mul_f32_e32 v157, 0xbfb8aa3b, v157
	v_exp_f32_e32 v157, v157
	v_pk_mul_f32 v[196:197], v[200:201], v[196:197]
	v_pk_add_f32 v[176:177], v[176:177], 1.0 op_sel_hi:[1,0]
	v_pk_mul_f32 v[66:67], v[66:67], v[196:197]
	v_lshlrev_b32_e32 v196, 16, v202
	v_and_b32_e32 v197, 0xffff0000, v202
	v_mul_f32_e32 v196, 0xbfb8aa3b, v196
	v_mul_f32_e32 v197, 0xbfb8aa3b, v197
	v_exp_f32_e32 v200, v196
	v_lshlrev_b32_e32 v196, 16, v198
	v_exp_f32_e32 v201, v197
	v_and_b32_e32 v197, 0xffff0000, v198
	v_lshlrev_b32_e32 v198, 16, v203
	v_mul_f32_e32 v198, 0xbfb8aa3b, v198
	v_exp_f32_e32 v202, v198
	v_lshlrev_b32_e32 v198, 16, v199
	v_and_b32_e32 v199, 0xffff0000, v199
	v_mul_f32_e32 v196, 0xbfb8aa3b, v196
	v_mul_f32_e32 v197, 0xbfb8aa3b, v197
	v_mul_f32_e32 v198, 0xbfb8aa3b, v198
	v_mul_f32_e32 v199, 0xbfb8aa3b, v199
	v_exp_f32_e32 v196, v196
	v_exp_f32_e32 v197, v197
	v_exp_f32_e32 v198, v198
	v_exp_f32_e32 v199, v199
	v_and_b32_e32 v203, 0xffff0000, v203
	v_mul_f32_e32 v203, 0xbfb8aa3b, v203
	v_add_f32_e32 v157, 1.0, v157
	v_add_f32_e32 v196, 1.0, v196
	v_add_f32_e32 v197, 1.0, v197
	v_add_f32_e32 v198, 1.0, v198
	v_exp_f32_e32 v203, v203
	v_add_f32_e32 v199, 1.0, v199
	v_rcp_f32_e32 v178, v157
	v_rcp_f32_e32 v196, v196
	v_rcp_f32_e32 v197, v197
	v_rcp_f32_e32 v198, v198
	v_rcp_f32_e32 v199, v199
	v_pk_add_f32 v[202:203], v[202:203], 1.0 op_sel_hi:[1,0]
	v_pk_add_f32 v[200:201], v[200:201], 1.0 op_sel_hi:[1,0]
	v_pk_mul_f32 v[176:177], v[176:177], v[178:179]
	v_pk_mul_f32 v[196:197], v[200:201], v[196:197]
	v_pk_mul_f32 v[198:199], v[202:203], v[198:199]
	v_pk_mul_f32 v[64:65], v[64:65], v[176:177]
	v_pk_mul_f32 v[62:63], v[62:63], v[198:199]
	v_pk_mul_f32 v[60:61], v[60:61], v[196:197]
	v_lshlrev_b32_e32 v157, 16, v208
	v_mul_f32_e32 v157, 0xbfb8aa3b, v157
	v_exp_f32_e32 v166, v157
	v_lshlrev_b32_e32 v157, 16, v204
	v_and_b32_e32 v204, 0xffff0000, v204
	v_mul_f32_e32 v204, 0xbfb8aa3b, v204
	v_exp_f32_e32 v204, v204
	v_and_b32_e32 v208, 0xffff0000, v208
	v_mul_f32_e32 v208, 0xbfb8aa3b, v208
	v_exp_f32_e32 v167, v208
	v_add_f32_e32 v204, 1.0, v204
	v_rcp_f32_e32 v169, v204
	v_lshlrev_b32_e32 v204, 16, v209
; #define MIXR(a_, b_) ((1.0f + __builtin_amdgcn_exp2f(-(b_) * LOG2E)) * __builtin_amdgcn_rcpf(1.0f + __builtin_amdgcn_exp2f(-(a_) * LOG2E)))
;     __device__ __forceinline__ void mid(f32x4 (&acc)[2][2][4][2], const Unit& u, int wr, int wc, int fr, int fq) const {
;         int row0 = u.pm * BM + wr * 64 + fr, col0 = u.pn * BM + wc * 32 + fq * 8;
;         asm volatile("" : "+v"(row0), "+v"(col0));
; #pragma unroll
;         for (int ai = 0; ai < 2; ++ai)
; #pragma unroll
;             for (int m = 0; m < 4; ++m) {
;                 const int row = row0 + ai * HALF + m * 16;
; #pragma unroll
;                 for (int bj = 0; bj < 2; ++bj) {
;                     const int col = col0 + bj * HALF;
;                     const u32x4 za = *(const u32x4*)(Z + (size_t)row * NZ + ZGA + col), zb = *(const u32x4*)(Z + (size_t)row * NZ + ZGB + col);
;     ...
;                     acc[ai][bj][m][0][0] *= MIXR(bflo(za.x), bflo(zb.x)); acc[ai][bj][m][0][1] *= MIXR(bfhi(za.x), bfhi(zb.x));
;                     acc[ai][bj][m][0][2] *= MIXR(bflo(za.y), bflo(zb.y)); acc[ai][bj][m][0][3] *= MIXR(bfhi(za.y), bfhi(zb.y));
;                     acc[ai][bj][m][1][0] *= MIXR(bflo(za.z), bflo(zb.z)); acc[ai][bj][m][1][1] *= MIXR(bfhi(za.z), bfhi(zb.z));
;                     acc[ai][bj][m][1][2] *= MIXR(bflo(za.w), bflo(zb.w)); acc[ai][bj][m][1][3] *= MIXR(bfhi(za.w), bfhi(zb.w));
;     ...
;                     asm volatile("" ::: "memory"); __builtin_amdgcn_sched_barrier(0);
;                 }
	v_mul_f32_e32 v204, 0xbfb8aa3b, v204
	v_exp_f32_e32 v208, v204
	v_lshlrev_b32_e32 v204, 16, v205
	v_and_b32_e32 v205, 0xffff0000, v205
	v_mul_f32_e32 v204, 0xbfb8aa3b, v204
	v_mul_f32_e32 v205, 0xbfb8aa3b, v205
	v_exp_f32_e32 v204, v204
	v_exp_f32_e32 v205, v205
	v_and_b32_e32 v209, 0xffff0000, v209
	v_mul_f32_e32 v209, 0xbfb8aa3b, v209
	v_add_f32_e32 v204, 1.0, v204
	v_exp_f32_e32 v209, v209
	v_add_f32_e32 v205, 1.0, v205
	v_rcp_f32_e32 v204, v204
	v_rcp_f32_e32 v205, v205
	v_pk_add_f32 v[208:209], v[208:209], 1.0 op_sel_hi:[1,0]
	v_mul_f32_e32 v157, 0xbfb8aa3b, v157
	v_exp_f32_e32 v157, v157
	v_pk_mul_f32 v[204:205], v[208:209], v[204:205]
	v_pk_add_f32 v[166:167], v[166:167], 1.0 op_sel_hi:[1,0]
	v_pk_mul_f32 v[58:59], v[58:59], v[204:205]
	v_lshlrev_b32_e32 v204, 16, v210
	v_and_b32_e32 v205, 0xffff0000, v210
	v_mul_f32_e32 v204, 0xbfb8aa3b, v204
	v_mul_f32_e32 v205, 0xbfb8aa3b, v205
	v_exp_f32_e32 v208, v204
	v_lshlrev_b32_e32 v204, 16, v206
	v_exp_f32_e32 v209, v205
	v_and_b32_e32 v205, 0xffff0000, v206
	v_lshlrev_b32_e32 v206, 16, v211
	v_mul_f32_e32 v206, 0xbfb8aa3b, v206
	v_exp_f32_e32 v210, v206
	v_lshlrev_b32_e32 v206, 16, v207
	v_and_b32_e32 v207, 0xffff0000, v207
	v_mul_f32_e32 v204, 0xbfb8aa3b, v204
	v_mul_f32_e32 v205, 0xbfb8aa3b, v205
	v_mul_f32_e32 v206, 0xbfb8aa3b, v206
	v_mul_f32_e32 v207, 0xbfb8aa3b, v207
	v_exp_f32_e32 v204, v204
	v_exp_f32_e32 v205, v205
	v_exp_f32_e32 v206, v206
	v_exp_f32_e32 v207, v207
	v_and_b32_e32 v211, 0xffff0000, v211
	v_mul_f32_e32 v211, 0xbfb8aa3b, v211
	v_add_f32_e32 v157, 1.0, v157
	v_add_f32_e32 v204, 1.0, v204
	v_add_f32_e32 v205, 1.0, v205
	v_add_f32_e32 v206, 1.0, v206
	v_exp_f32_e32 v211, v211
	v_add_f32_e32 v207, 1.0, v207
	v_rcp_f32_e32 v168, v157
	v_rcp_f32_e32 v204, v204
	v_rcp_f32_e32 v205, v205
	v_rcp_f32_e32 v206, v206
	v_rcp_f32_e32 v207, v207
	v_pk_add_f32 v[210:211], v[210:211], 1.0 op_sel_hi:[1,0]
	v_pk_add_f32 v[208:209], v[208:209], 1.0 op_sel_hi:[1,0]
	v_pk_mul_f32 v[166:167], v[166:167], v[168:169]
	v_pk_mul_f32 v[204:205], v[208:209], v[204:205]
	v_pk_mul_f32 v[206:207], v[210:211], v[206:207]
	v_pk_mul_f32 v[56:57], v[56:57], v[166:167]
	v_pk_mul_f32 v[54:55], v[54:55], v[206:207]
	v_pk_mul_f32 v[52:53], v[52:53], v[204:205]
	v_add_u32_e32 v132, 0x90, v1
	v_mad_i64_i32 v[132:133], s[8:9], v132, s16, v[2:3]
	v_lshl_add_u64 v[136:137], v[132:133], 0, v[164:165]
	v_add_co_u32_e32 v138, vcc, s17, v136
	v_lshl_add_u64 v[166:167], v[136:137], 0, s[48:49]
	s_nop 0
	v_addc_co_u32_e32 v139, vcc, 0, v137, vcc
	v_lshl_add_u64 v[168:169], v[136:137], 0, s[46:47]
	v_add_u32_e32 v159, 0x2d6000, v0
	global_load_dwordx4 v[196:199], v159, s[2:3]
	global_load_dwordx4 v[200:203], v159, s[2:3] offset:2048
	global_load_dwordx4 v[204:207], v159, s[2:3] offset:256
	global_load_dwordx4 v[208:211], v159, s[2:3] offset:2304
	s_waitcnt vmcnt(8)
	v_lshlrev_b32_e32 v157, 16, v216
	v_mul_f32_e32 v157, 0xbfb8aa3b, v157
	v_exp_f32_e32 v176, v157
	v_lshlrev_b32_e32 v157, 16, v212
	v_and_b32_e32 v212, 0xffff0000, v212
	v_mul_f32_e32 v212, 0xbfb8aa3b, v212
	v_exp_f32_e32 v212, v212
	v_and_b32_e32 v216, 0xffff0000, v216
	v_mul_f32_e32 v216, 0xbfb8aa3b, v216
	v_exp_f32_e32 v177, v216
	v_add_f32_e32 v212, 1.0, v212
	v_rcp_f32_e32 v179, v212
	v_lshlrev_b32_e32 v212, 16, v217
	v_mul_f32_e32 v212, 0xbfb8aa3b, v212
	v_exp_f32_e32 v216, v212
	v_lshlrev_b32_e32 v212, 16, v213
	v_and_b32_e32 v213, 0xffff0000, v213
	v_mul_f32_e32 v212, 0xbfb8aa3b, v212
	v_mul_f32_e32 v213, 0xbfb8aa3b, v213
	v_exp_f32_e32 v212, v212
	v_exp_f32_e32 v213, v213
	v_and_b32_e32 v217, 0xffff0000, v217
	v_mul_f32_e32 v217, 0xbfb8aa3b, v217
	v_add_f32_e32 v212, 1.0, v212
	v_exp_f32_e32 v217, v217
	v_add_f32_e32 v213, 1.0, v213
	v_rcp_f32_e32 v212, v212
	v_rcp_f32_e32 v213, v213
	v_pk_add_f32 v[216:217], v[216:217], 1.0 op_sel_hi:[1,0]
	v_mul_f32_e32 v157, 0xbfb8aa3b, v157
	v_exp_f32_e32 v157, v157
	v_pk_mul_f32 v[212:213], v[216:217], v[212:213]
	v_pk_add_f32 v[176:177], v[176:177], 1.0 op_sel_hi:[1,0]
	v_pk_mul_f32 v[50:51], v[50:51], v[212:213]
	v_lshlrev_b32_e32 v212, 16, v218
	v_and_b32_e32 v213, 0xffff0000, v218
	v_mul_f32_e32 v212, 0xbfb8aa3b, v212
	v_mul_f32_e32 v213, 0xbfb8aa3b, v213
	v_exp_f32_e32 v216, v212
	v_lshlrev_b32_e32 v212, 16, v214
	v_exp_f32_e32 v217, v213
	v_and_b32_e32 v213, 0xffff0000, v214
	v_lshlrev_b32_e32 v214, 16, v219
	v_mul_f32_e32 v214, 0xbfb8aa3b, v214
	v_exp_f32_e32 v218, v214
	v_lshlrev_b32_e32 v214, 16, v215
	v_and_b32_e32 v215, 0xffff0000, v215
	v_mul_f32_e32 v212, 0xbfb8aa3b, v212
	v_mul_f32_e32 v213, 0xbfb8aa3b, v213
	v_mul_f32_e32 v214, 0xbfb8aa3b, v214
	v_mul_f32_e32 v215, 0xbfb8aa3b, v215
	v_exp_f32_e32 v212, v212
	v_exp_f32_e32 v213, v213
	v_exp_f32_e32 v214, v214
	v_exp_f32_e32 v215, v215
	v_and_b32_e32 v219, 0xffff0000, v219
	v_mul_f32_e32 v219, 0xbfb8aa3b, v219
	v_add_f32_e32 v157, 1.0, v157
	v_add_f32_e32 v212, 1.0, v212
	v_add_f32_e32 v213, 1.0, v213
	v_add_f32_e32 v214, 1.0, v214
	v_exp_f32_e32 v219, v219
	v_add_f32_e32 v215, 1.0, v215
	v_rcp_f32_e32 v178, v157
	v_rcp_f32_e32 v212, v212
	v_rcp_f32_e32 v213, v213
	v_rcp_f32_e32 v214, v214
	v_rcp_f32_e32 v215, v215
	v_pk_add_f32 v[218:219], v[218:219], 1.0 op_sel_hi:[1,0]
	v_pk_add_f32 v[216:217], v[216:217], 1.0 op_sel_hi:[1,0]
	v_pk_mul_f32 v[176:177], v[176:177], v[178:179]
	v_pk_mul_f32 v[212:213], v[216:217], v[212:213]
	v_pk_mul_f32 v[214:215], v[218:219], v[214:215]
	v_pk_mul_f32 v[48:49], v[48:49], v[176:177]
	v_pk_mul_f32 v[46:47], v[46:47], v[214:215]
	v_pk_mul_f32 v[44:45], v[44:45], v[212:213]
	v_lshlrev_b32_e32 v157, 16, v224
	v_mul_f32_e32 v157, 0xbfb8aa3b, v157
	v_exp_f32_e32 v166, v157
	v_lshlrev_b32_e32 v157, 16, v220
; #define MIXR(a_, b_) ((1.0f + __builtin_amdgcn_exp2f(-(b_) * LOG2E)) * __builtin_amdgcn_rcpf(1.0f + __builtin_amdgcn_exp2f(-(a_) * LOG2E)))
;     __device__ __forceinline__ void mid(f32x4 (&acc)[2][2][4][2], const Unit& u, int wr, int wc, int fr, int fq) const {
;         int row0 = u.pm * BM + wr * 64 + fr, col0 = u.pn * BM + wc * 32 + fq * 8;
;         asm volatile("" : "+v"(row0), "+v"(col0));
; #pragma unroll
;         for (int ai = 0; ai < 2; ++ai)
; #pragma unroll
;             for (int m = 0; m < 4; ++m) {
;                 const int row = row0 + ai * HALF + m * 16;
; #pragma unroll
;                 for (int bj = 0; bj < 2; ++bj) {
;                     const int col = col0 + bj * HALF;
;                     const u32x4 za = *(const u32x4*)(Z + (size_t)row * NZ + ZGA + col), zb = *(const u32x4*)(Z + (size_t)row * NZ + ZGB + col);
;     ...
;                     acc[ai][bj][m][0][0] *= MIXR(bflo(za.x), bflo(zb.x)); acc[ai][bj][m][0][1] *= MIXR(bfhi(za.x), bfhi(zb.x));
;                     acc[ai][bj][m][0][2] *= MIXR(bflo(za.y), bflo(zb.y)); acc[ai][bj][m][0][3] *= MIXR(bfhi(za.y), bfhi(zb.y));
;                     acc[ai][bj][m][1][0] *= MIXR(bflo(za.z), bflo(zb.z)); acc[ai][bj][m][1][1] *= MIXR(bfhi(za.z), bfhi(zb.z));
;                     acc[ai][bj][m][1][2] *= MIXR(bflo(za.w), bflo(zb.w)); acc[ai][bj][m][1][3] *= MIXR(bfhi(za.w), bfhi(zb.w));
;     ...
;                     asm volatile("" ::: "memory"); __builtin_amdgcn_sched_barrier(0);
;                 }
	v_and_b32_e32 v220, 0xffff0000, v220
	v_mul_f32_e32 v220, 0xbfb8aa3b, v220
	v_exp_f32_e32 v220, v220
	v_and_b32_e32 v224, 0xffff0000, v224
	v_mul_f32_e32 v224, 0xbfb8aa3b, v224
	v_exp_f32_e32 v167, v224
	v_add_f32_e32 v220, 1.0, v220
	v_rcp_f32_e32 v169, v220
	v_lshlrev_b32_e32 v220, 16, v225
	v_mul_f32_e32 v220, 0xbfb8aa3b, v220
	v_exp_f32_e32 v224, v220
	v_lshlrev_b32_e32 v220, 16, v221
	v_and_b32_e32 v221, 0xffff0000, v221
	v_mul_f32_e32 v220, 0xbfb8aa3b, v220
	v_mul_f32_e32 v221, 0xbfb8aa3b, v221
	v_exp_f32_e32 v220, v220
	v_exp_f32_e32 v221, v221
	v_and_b32_e32 v225, 0xffff0000, v225
	v_mul_f32_e32 v225, 0xbfb8aa3b, v225
	v_add_f32_e32 v220, 1.0, v220
	v_exp_f32_e32 v225, v225
	v_add_f32_e32 v221, 1.0, v221
	v_rcp_f32_e32 v220, v220
	v_rcp_f32_e32 v221, v221
	v_pk_add_f32 v[224:225], v[224:225], 1.0 op_sel_hi:[1,0]
	v_mul_f32_e32 v157, 0xbfb8aa3b, v157
	v_exp_f32_e32 v157, v157
	v_pk_mul_f32 v[220:221], v[224:225], v[220:221]
	v_pk_add_f32 v[166:167], v[166:167], 1.0 op_sel_hi:[1,0]
	v_pk_mul_f32 v[42:43], v[42:43], v[220:221]
	v_lshlrev_b32_e32 v220, 16, v226
	v_and_b32_e32 v221, 0xffff0000, v226
	v_mul_f32_e32 v220, 0xbfb8aa3b, v220
	v_mul_f32_e32 v221, 0xbfb8aa3b, v221
	v_exp_f32_e32 v224, v220
	v_lshlrev_b32_e32 v220, 16, v222
	v_exp_f32_e32 v225, v221
	v_and_b32_e32 v221, 0xffff0000, v222
	v_lshlrev_b32_e32 v222, 16, v227
	v_mul_f32_e32 v222, 0xbfb8aa3b, v222
	v_exp_f32_e32 v226, v222
	v_lshlrev_b32_e32 v222, 16, v223
	v_and_b32_e32 v223, 0xffff0000, v223
	v_mul_f32_e32 v220, 0xbfb8aa3b, v220
	v_mul_f32_e32 v221, 0xbfb8aa3b, v221
	v_mul_f32_e32 v222, 0xbfb8aa3b, v222
	v_mul_f32_e32 v223, 0xbfb8aa3b, v223
	v_exp_f32_e32 v220, v220
	v_exp_f32_e32 v221, v221
	v_exp_f32_e32 v222, v222
	v_exp_f32_e32 v223, v223
	v_and_b32_e32 v227, 0xffff0000, v227
	v_mul_f32_e32 v227, 0xbfb8aa3b, v227
	v_add_f32_e32 v157, 1.0, v157
	v_add_f32_e32 v220, 1.0, v220
	v_add_f32_e32 v221, 1.0, v221
	v_add_f32_e32 v222, 1.0, v222
	v_exp_f32_e32 v227, v227
	v_add_f32_e32 v223, 1.0, v223
	v_rcp_f32_e32 v168, v157
	v_rcp_f32_e32 v220, v220
	v_rcp_f32_e32 v221, v221
	v_rcp_f32_e32 v222, v222
	v_rcp_f32_e32 v223, v223
	v_pk_add_f32 v[226:227], v[226:227], 1.0 op_sel_hi:[1,0]
	v_pk_add_f32 v[224:225], v[224:225], 1.0 op_sel_hi:[1,0]
	v_pk_mul_f32 v[166:167], v[166:167], v[168:169]
	v_pk_mul_f32 v[220:221], v[224:225], v[220:221]
	v_pk_mul_f32 v[222:223], v[226:227], v[222:223]
	v_pk_mul_f32 v[40:41], v[40:41], v[166:167]
	v_pk_mul_f32 v[38:39], v[38:39], v[222:223]
	v_pk_mul_f32 v[36:37], v[36:37], v[220:221]
	v_add_u32_e32 v132, 0xa0, v1
	v_mad_i64_i32 v[132:133], s[8:9], v132, s16, v[2:3]
	v_lshl_add_u64 v[136:137], v[132:133], 0, v[164:165]
	v_add_co_u32_e32 v138, vcc, s17, v136
	v_lshl_add_u64 v[166:167], v[136:137], 0, s[48:49]
	s_nop 0
	v_addc_co_u32_e32 v139, vcc, 0, v137, vcc
	v_lshl_add_u64 v[168:169], v[136:137], 0, s[46:47]
	s_waitcnt vmcnt(4)
	v_lshlrev_b32_e32 v157, 16, v184
	v_mul_f32_e32 v157, 0xbfb8aa3b, v157
	v_exp_f32_e32 v176, v157
	v_lshlrev_b32_e32 v157, 16, v180
	v_and_b32_e32 v180, 0xffff0000, v180
	v_mul_f32_e32 v180, 0xbfb8aa3b, v180
	v_exp_f32_e32 v180, v180
	v_and_b32_e32 v184, 0xffff0000, v184
	v_mul_f32_e32 v184, 0xbfb8aa3b, v184
	v_exp_f32_e32 v177, v184
	v_add_f32_e32 v180, 1.0, v180
	v_rcp_f32_e32 v179, v180
	v_lshlrev_b32_e32 v180, 16, v185
	v_mul_f32_e32 v180, 0xbfb8aa3b, v180
	v_exp_f32_e32 v184, v180
	v_lshlrev_b32_e32 v180, 16, v181
	v_and_b32_e32 v181, 0xffff0000, v181
	v_mul_f32_e32 v180, 0xbfb8aa3b, v180
	v_mul_f32_e32 v181, 0xbfb8aa3b, v181
	v_exp_f32_e32 v180, v180
	v_exp_f32_e32 v181, v181
	v_and_b32_e32 v185, 0xffff0000, v185
	v_mul_f32_e32 v185, 0xbfb8aa3b, v185
	v_add_f32_e32 v180, 1.0, v180
	v_exp_f32_e32 v185, v185
	v_add_f32_e32 v181, 1.0, v181
	v_rcp_f32_e32 v180, v180
	v_rcp_f32_e32 v181, v181
	v_pk_add_f32 v[184:185], v[184:185], 1.0 op_sel_hi:[1,0]
	v_mul_f32_e32 v157, 0xbfb8aa3b, v157
	v_exp_f32_e32 v157, v157
	v_pk_mul_f32 v[180:181], v[184:185], v[180:181]
	v_pk_add_f32 v[176:177], v[176:177], 1.0 op_sel_hi:[1,0]
	v_pk_mul_f32 v[34:35], v[34:35], v[180:181]
	v_lshlrev_b32_e32 v180, 16, v186
	v_and_b32_e32 v181, 0xffff0000, v186
	v_mul_f32_e32 v180, 0xbfb8aa3b, v180
	v_mul_f32_e32 v181, 0xbfb8aa3b, v181
	v_exp_f32_e32 v184, v180
	v_lshlrev_b32_e32 v180, 16, v182
	v_exp_f32_e32 v185, v181
	v_and_b32_e32 v181, 0xffff0000, v182
	v_lshlrev_b32_e32 v182, 16, v187
	v_mul_f32_e32 v182, 0xbfb8aa3b, v182
	v_exp_f32_e32 v186, v182
	v_lshlrev_b32_e32 v182, 16, v183
	v_and_b32_e32 v183, 0xffff0000, v183
	v_mul_f32_e32 v180, 0xbfb8aa3b, v180
	v_mul_f32_e32 v181, 0xbfb8aa3b, v181
	v_mul_f32_e32 v182, 0xbfb8aa3b, v182
	v_mul_f32_e32 v183, 0xbfb8aa3b, v183
	v_exp_f32_e32 v180, v180
	v_exp_f32_e32 v181, v181
	v_exp_f32_e32 v182, v182
	v_exp_f32_e32 v183, v183
	v_and_b32_e32 v187, 0xffff0000, v187
	v_mul_f32_e32 v187, 0xbfb8aa3b, v187
	v_add_f32_e32 v157, 1.0, v157
	v_add_f32_e32 v180, 1.0, v180
	v_add_f32_e32 v181, 1.0, v181
	v_add_f32_e32 v182, 1.0, v182
	v_exp_f32_e32 v187, v187
	v_add_f32_e32 v183, 1.0, v183
	v_rcp_f32_e32 v178, v157
	v_rcp_f32_e32 v180, v180
	v_rcp_f32_e32 v181, v181
	v_rcp_f32_e32 v182, v182
	v_rcp_f32_e32 v183, v183
	v_pk_add_f32 v[186:187], v[186:187], 1.0 op_sel_hi:[1,0]
	v_pk_add_f32 v[184:185], v[184:185], 1.0 op_sel_hi:[1,0]
	v_pk_mul_f32 v[176:177], v[176:177], v[178:179]
	v_pk_mul_f32 v[180:181], v[184:185], v[180:181]
	v_pk_mul_f32 v[182:183], v[186:187], v[182:183]
	v_pk_mul_f32 v[32:33], v[32:33], v[176:177]
	v_pk_mul_f32 v[30:31], v[30:31], v[182:183]
	v_pk_mul_f32 v[28:29], v[28:29], v[180:181]
	v_lshlrev_b32_e32 v157, 16, v192
	v_mul_f32_e32 v157, 0xbfb8aa3b, v157
	v_exp_f32_e32 v166, v157
; #define MIXR(a_, b_) ((1.0f + __builtin_amdgcn_exp2f(-(b_) * LOG2E)) * __builtin_amdgcn_rcpf(1.0f + __builtin_amdgcn_exp2f(-(a_) * LOG2E)))
;     __device__ __forceinline__ void mid(f32x4 (&acc)[2][2][4][2], const Unit& u, int wr, int wc, int fr, int fq) const {
;         int row0 = u.pm * BM + wr * 64 + fr, col0 = u.pn * BM + wc * 32 + fq * 8;
;         asm volatile("" : "+v"(row0), "+v"(col0));
; #pragma unroll
;         for (int ai = 0; ai < 2; ++ai)
; #pragma unroll
;             for (int m = 0; m < 4; ++m) {
;                 const int row = row0 + ai * HALF + m * 16;
; #pragma unroll
;                 for (int bj = 0; bj < 2; ++bj) {
;                     const int col = col0 + bj * HALF;
;                     const u32x4 za = *(const u32x4*)(Z + (size_t)row * NZ + ZGA + col), zb = *(const u32x4*)(Z + (size_t)row * NZ + ZGB + col);
;     ...
;                     acc[ai][bj][m][0][0] *= MIXR(bflo(za.x), bflo(zb.x)); acc[ai][bj][m][0][1] *= MIXR(bfhi(za.x), bfhi(zb.x));
;                     acc[ai][bj][m][0][2] *= MIXR(bflo(za.y), bflo(zb.y)); acc[ai][bj][m][0][3] *= MIXR(bfhi(za.y), bfhi(zb.y));
;                     acc[ai][bj][m][1][0] *= MIXR(bflo(za.z), bflo(zb.z)); acc[ai][bj][m][1][1] *= MIXR(bfhi(za.z), bfhi(zb.z));
;                     acc[ai][bj][m][1][2] *= MIXR(bflo(za.w), bflo(zb.w)); acc[ai][bj][m][1][3] *= MIXR(bfhi(za.w), bfhi(zb.w));
;     ...
;                     asm volatile("" ::: "memory"); __builtin_amdgcn_sched_barrier(0);
;                 }
	v_lshlrev_b32_e32 v157, 16, v188
	v_and_b32_e32 v188, 0xffff0000, v188
	v_mul_f32_e32 v188, 0xbfb8aa3b, v188
	v_exp_f32_e32 v188, v188
	v_and_b32_e32 v192, 0xffff0000, v192
	v_mul_f32_e32 v192, 0xbfb8aa3b, v192
	v_exp_f32_e32 v167, v192
	v_add_f32_e32 v188, 1.0, v188
	v_rcp_f32_e32 v169, v188
	v_lshlrev_b32_e32 v188, 16, v193
	v_mul_f32_e32 v188, 0xbfb8aa3b, v188
	v_exp_f32_e32 v192, v188
	v_lshlrev_b32_e32 v188, 16, v189
	v_and_b32_e32 v189, 0xffff0000, v189
	v_mul_f32_e32 v188, 0xbfb8aa3b, v188
	v_mul_f32_e32 v189, 0xbfb8aa3b, v189
	v_exp_f32_e32 v188, v188
	v_exp_f32_e32 v189, v189
	v_and_b32_e32 v193, 0xffff0000, v193
	v_mul_f32_e32 v193, 0xbfb8aa3b, v193
	v_add_f32_e32 v188, 1.0, v188
	v_exp_f32_e32 v193, v193
	v_add_f32_e32 v189, 1.0, v189
	v_rcp_f32_e32 v188, v188
	v_rcp_f32_e32 v189, v189
	v_pk_add_f32 v[192:193], v[192:193], 1.0 op_sel_hi:[1,0]
	v_mul_f32_e32 v157, 0xbfb8aa3b, v157
	v_exp_f32_e32 v157, v157
	v_pk_mul_f32 v[188:189], v[192:193], v[188:189]
	v_pk_add_f32 v[166:167], v[166:167], 1.0 op_sel_hi:[1,0]
	v_pk_mul_f32 v[26:27], v[26:27], v[188:189]
	v_lshlrev_b32_e32 v188, 16, v194
	v_and_b32_e32 v189, 0xffff0000, v194
	v_mul_f32_e32 v188, 0xbfb8aa3b, v188
	v_mul_f32_e32 v189, 0xbfb8aa3b, v189
	v_exp_f32_e32 v192, v188
	v_lshlrev_b32_e32 v188, 16, v190
	v_exp_f32_e32 v193, v189
	v_and_b32_e32 v189, 0xffff0000, v190
	v_lshlrev_b32_e32 v190, 16, v195
	v_mul_f32_e32 v190, 0xbfb8aa3b, v190
	v_exp_f32_e32 v194, v190
	v_lshlrev_b32_e32 v190, 16, v191
	v_and_b32_e32 v191, 0xffff0000, v191
	v_mul_f32_e32 v188, 0xbfb8aa3b, v188
	v_mul_f32_e32 v189, 0xbfb8aa3b, v189
	v_mul_f32_e32 v190, 0xbfb8aa3b, v190
	v_mul_f32_e32 v191, 0xbfb8aa3b, v191
	v_exp_f32_e32 v188, v188
	v_exp_f32_e32 v189, v189
	v_exp_f32_e32 v190, v190
	v_exp_f32_e32 v191, v191
	v_and_b32_e32 v195, 0xffff0000, v195
	v_mul_f32_e32 v195, 0xbfb8aa3b, v195
	v_add_f32_e32 v157, 1.0, v157
	v_add_f32_e32 v188, 1.0, v188
	v_add_f32_e32 v189, 1.0, v189
	v_add_f32_e32 v190, 1.0, v190
	v_exp_f32_e32 v195, v195
	v_add_f32_e32 v191, 1.0, v191
	v_rcp_f32_e32 v168, v157
	v_rcp_f32_e32 v188, v188
	v_rcp_f32_e32 v189, v189
	v_rcp_f32_e32 v190, v190
	v_rcp_f32_e32 v191, v191
	v_pk_add_f32 v[194:195], v[194:195], 1.0 op_sel_hi:[1,0]
	v_pk_add_f32 v[192:193], v[192:193], 1.0 op_sel_hi:[1,0]
	v_pk_mul_f32 v[166:167], v[166:167], v[168:169]
	v_pk_mul_f32 v[188:189], v[192:193], v[188:189]
	v_pk_mul_f32 v[190:191], v[194:195], v[190:191]
	v_pk_mul_f32 v[24:25], v[24:25], v[166:167]
	v_pk_mul_f32 v[22:23], v[22:23], v[190:191]
	v_pk_mul_f32 v[20:21], v[20:21], v[188:189]
	v_add_u32_e32 v1, 0xb0, v1
	v_mad_i64_i32 v[2:3], s[8:9], v1, s16, v[2:3]
	v_lshl_add_u64 v[136:137], v[2:3], 0, v[164:165]
	v_add_co_u32_e32 v138, vcc, s17, v136
	v_lshl_add_u64 v[2:3], v[136:137], 0, s[48:49]
	s_nop 0
	v_addc_co_u32_e32 v139, vcc, 0, v137, vcc
	v_lshl_add_u64 v[164:165], v[136:137], 0, s[46:47]
	s_waitcnt vmcnt(0)
; #define MIXR(a_, b_) ((1.0f + __builtin_amdgcn_exp2f(-(b_) * LOG2E)) * __builtin_amdgcn_rcpf(1.0f + __builtin_amdgcn_exp2f(-(a_) * LOG2E)))
;     __device__ __forceinline__ void mid(f32x4 (&acc)[2][2][4][2], const Unit& u, int wr, int wc, int fr, int fq) const {
;         int row0 = u.pm * BM + wr * 64 + fr, col0 = u.pn * BM + wc * 32 + fq * 8;
;         asm volatile("" : "+v"(row0), "+v"(col0));
; #pragma unroll
;         for (int ai = 0; ai < 2; ++ai)
; #pragma unroll
;             for (int m = 0; m < 4; ++m) {
;                 const int row = row0 + ai * HALF + m * 16;
; #pragma unroll
;                 for (int bj = 0; bj < 2; ++bj) {
;                     const int col = col0 + bj * HALF;
;                     const u32x4 za = *(const u32x4*)(Z + (size_t)row * NZ + ZGA + col), zb = *(const u32x4*)(Z + (size_t)row * NZ + ZGB + col);
;     ...
;                     acc[ai][bj][m][0][0] *= MIXR(bflo(za.x), bflo(zb.x)); acc[ai][bj][m][0][1] *= MIXR(bfhi(za.x), bfhi(zb.x));
;                     acc[ai][bj][m][0][2] *= MIXR(bflo(za.y), bflo(zb.y)); acc[ai][bj][m][0][3] *= MIXR(bfhi(za.y), bfhi(zb.y));
;                     acc[ai][bj][m][1][0] *= MIXR(bflo(za.z), bflo(zb.z)); acc[ai][bj][m][1][1] *= MIXR(bfhi(za.z), bfhi(zb.z));
;                     acc[ai][bj][m][1][2] *= MIXR(bflo(za.w), bflo(zb.w)); acc[ai][bj][m][1][3] *= MIXR(bfhi(za.w), bfhi(zb.w));
;     ...
;                     asm volatile("" ::: "memory"); __builtin_amdgcn_sched_barrier(0);
;                 }
	v_lshlrev_b32_e32 v1, 16, v200
	v_mul_f32_e32 v1, 0xbfb8aa3b, v1
	v_exp_f32_e32 v166, v1
	v_lshlrev_b32_e32 v1, 16, v196
	v_mul_f32_e32 v1, 0xbfb8aa3b, v1
	v_exp_f32_e32 v1, v1
	s_nop 0
	v_add_f32_e32 v1, 1.0, v1
	v_rcp_f32_e32 v168, v1
	v_and_b32_e32 v1, 0xffff0000, v200
	v_mul_f32_e32 v1, 0xbfb8aa3b, v1
	v_exp_f32_e32 v167, v1
	v_and_b32_e32 v1, 0xffff0000, v196
	v_mul_f32_e32 v1, 0xbfb8aa3b, v1
	v_exp_f32_e32 v1, v1
	v_pk_add_f32 v[166:167], v[166:167], 1.0 op_sel_hi:[1,0]
	v_add_f32_e32 v1, 1.0, v1
	v_rcp_f32_e32 v169, v1
	v_lshlrev_b32_e32 v1, 16, v201
	v_mul_f32_e32 v1, 0xbfb8aa3b, v1
	v_exp_f32_e32 v200, v1
	v_lshlrev_b32_e32 v1, 16, v197
	v_mul_f32_e32 v1, 0xbfb8aa3b, v1
	v_exp_f32_e32 v1, v1
	v_pk_mul_f32 v[166:167], v[166:167], v[168:169]
	v_add_f32_e32 v1, 1.0, v1
	v_rcp_f32_e32 v196, v1
	v_and_b32_e32 v1, 0xffff0000, v201
	v_mul_f32_e32 v1, 0xbfb8aa3b, v1
	v_exp_f32_e32 v201, v1
	v_and_b32_e32 v1, 0xffff0000, v197
	v_mul_f32_e32 v1, 0xbfb8aa3b, v1
	v_exp_f32_e32 v1, v1
	v_pk_add_f32 v[200:201], v[200:201], 1.0 op_sel_hi:[1,0]
	v_pk_mul_f32 v[16:17], v[16:17], v[166:167]
	v_add_f32_e32 v1, 1.0, v1
	v_rcp_f32_e32 v197, v1
	v_lshlrev_b32_e32 v1, 16, v202
	v_mul_f32_e32 v1, 0xbfb8aa3b, v1
	v_pk_mul_f32 v[196:197], v[200:201], v[196:197]
	v_exp_f32_e32 v200, v1
	v_lshlrev_b32_e32 v1, 16, v198
	v_mul_f32_e32 v1, 0xbfb8aa3b, v1
	v_exp_f32_e32 v1, v1
	v_pk_mul_f32 v[18:19], v[18:19], v[196:197]
	v_add_f32_e32 v1, 1.0, v1
	v_rcp_f32_e32 v196, v1
	v_and_b32_e32 v1, 0xffff0000, v202
	v_mul_f32_e32 v1, 0xbfb8aa3b, v1
	v_exp_f32_e32 v201, v1
	v_and_b32_e32 v1, 0xffff0000, v198
	v_mul_f32_e32 v1, 0xbfb8aa3b, v1
	v_exp_f32_e32 v1, v1
	v_pk_add_f32 v[200:201], v[200:201], 1.0 op_sel_hi:[1,0]
	v_add_f32_e32 v1, 1.0, v1
	v_rcp_f32_e32 v197, v1
	v_lshlrev_b32_e32 v1, 16, v203
	v_mul_f32_e32 v1, 0xbfb8aa3b, v1
	v_exp_f32_e32 v202, v1
	v_lshlrev_b32_e32 v1, 16, v199
	v_mul_f32_e32 v1, 0xbfb8aa3b, v1
	v_exp_f32_e32 v1, v1
	v_pk_mul_f32 v[196:197], v[200:201], v[196:197]
	v_add_f32_e32 v1, 1.0, v1
	v_rcp_f32_e32 v198, v1
	v_and_b32_e32 v1, 0xffff0000, v203
	v_mul_f32_e32 v1, 0xbfb8aa3b, v1
	v_exp_f32_e32 v203, v1
	v_and_b32_e32 v1, 0xffff0000, v199
	v_mul_f32_e32 v1, 0xbfb8aa3b, v1
	v_exp_f32_e32 v1, v1
	v_pk_add_f32 v[202:203], v[202:203], 1.0 op_sel_hi:[1,0]
	v_pk_mul_f32 v[12:13], v[12:13], v[196:197]
	v_add_f32_e32 v1, 1.0, v1
	v_rcp_f32_e32 v199, v1
	s_nop 0
	v_pk_mul_f32 v[198:199], v[202:203], v[198:199]
	s_nop 0
	v_pk_mul_f32 v[14:15], v[14:15], v[198:199]
	v_lshlrev_b32_e32 v1, 16, v208
	v_mul_f32_e32 v1, 0xbfb8aa3b, v1
	v_exp_f32_e32 v2, v1
	v_lshlrev_b32_e32 v1, 16, v204
	v_mul_f32_e32 v1, 0xbfb8aa3b, v1
	v_exp_f32_e32 v1, v1
	s_nop 0
	v_add_f32_e32 v1, 1.0, v1
	v_rcp_f32_e32 v164, v1
	v_and_b32_e32 v1, 0xffff0000, v208
	v_mul_f32_e32 v1, 0xbfb8aa3b, v1
	v_exp_f32_e32 v3, v1
	v_and_b32_e32 v1, 0xffff0000, v204
	v_mul_f32_e32 v1, 0xbfb8aa3b, v1
	v_exp_f32_e32 v1, v1
	v_pk_add_f32 v[2:3], v[2:3], 1.0 op_sel_hi:[1,0]
	v_add_f32_e32 v1, 1.0, v1
	v_rcp_f32_e32 v165, v1
	v_lshlrev_b32_e32 v1, 16, v209
	v_mul_f32_e32 v1, 0xbfb8aa3b, v1
	v_exp_f32_e32 v208, v1
	v_lshlrev_b32_e32 v1, 16, v205
	v_mul_f32_e32 v1, 0xbfb8aa3b, v1
	v_exp_f32_e32 v1, v1
	v_pk_mul_f32 v[2:3], v[2:3], v[164:165]
	v_add_f32_e32 v1, 1.0, v1
	v_rcp_f32_e32 v204, v1
	v_and_b32_e32 v1, 0xffff0000, v209
	v_mul_f32_e32 v1, 0xbfb8aa3b, v1
	v_exp_f32_e32 v209, v1
	v_and_b32_e32 v1, 0xffff0000, v205
	v_mul_f32_e32 v1, 0xbfb8aa3b, v1
	v_exp_f32_e32 v1, v1
	v_pk_add_f32 v[208:209], v[208:209], 1.0 op_sel_hi:[1,0]
	v_pk_mul_f32 v[8:9], v[8:9], v[2:3]
	v_add_f32_e32 v1, 1.0, v1
	v_rcp_f32_e32 v205, v1
	v_lshlrev_b32_e32 v1, 16, v210
	v_mul_f32_e32 v1, 0xbfb8aa3b, v1
	v_pk_mul_f32 v[204:205], v[208:209], v[204:205]
	s_nop 0
	v_pk_mul_f32 v[10:11], v[10:11], v[204:205]
	v_exp_f32_e32 v204, v1
	v_lshlrev_b32_e32 v1, 16, v206
	v_mul_f32_e32 v1, 0xbfb8aa3b, v1
	v_exp_f32_e32 v1, v1
	s_nop 0
	v_add_f32_e32 v1, 1.0, v1
	v_rcp_f32_e32 v2, v1
	v_and_b32_e32 v1, 0xffff0000, v210
	v_mul_f32_e32 v1, 0xbfb8aa3b, v1
	v_exp_f32_e32 v205, v1
	v_and_b32_e32 v1, 0xffff0000, v206
	v_mul_f32_e32 v1, 0xbfb8aa3b, v1
	v_exp_f32_e32 v1, v1
	v_pk_add_f32 v[204:205], v[204:205], 1.0 op_sel_hi:[1,0]
	v_add_f32_e32 v1, 1.0, v1
	v_rcp_f32_e32 v3, v1
	v_lshlrev_b32_e32 v1, 16, v211
	v_mul_f32_e32 v1, 0xbfb8aa3b, v1
	v_exp_f32_e32 v208, v1
	v_lshlrev_b32_e32 v1, 16, v207
	v_mul_f32_e32 v1, 0xbfb8aa3b, v1
	v_exp_f32_e32 v1, v1
	v_pk_mul_f32 v[2:3], v[204:205], v[2:3]
	v_add_f32_e32 v1, 1.0, v1
	v_rcp_f32_e32 v206, v1
	v_and_b32_e32 v1, 0xffff0000, v211
	v_mul_f32_e32 v1, 0xbfb8aa3b, v1
	v_exp_f32_e32 v209, v1
	v_and_b32_e32 v1, 0xffff0000, v207
	v_mul_f32_e32 v1, 0xbfb8aa3b, v1
	v_exp_f32_e32 v1, v1
	v_pk_add_f32 v[208:209], v[208:209], 1.0 op_sel_hi:[1,0]
	v_pk_mul_f32 v[4:5], v[4:5], v[2:3]
	v_add_f32_e32 v1, 1.0, v1
	v_rcp_f32_e32 v207, v1
	s_nop 0
	v_pk_mul_f32 v[204:205], v[208:209], v[206:207]
	s_nop 0
	v_pk_mul_f32 v[6:7], v[6:7], v[204:205]
	s_branch .LBB0_926

; __device__ __forceinline__ float sigmoidf_(float x) { return __builtin_amdgcn_rcpf(1.0f + __builtin_amdgcn_exp2f(-x * LOG2E)); }
; __device__ __forceinline__ unsigned cvt_pk_bf16(float lo, float hi) { unsigned r; asm volatile("v_cvt_pk_bf16_f32 %0, %1, %2" : "=v"(r) : "v"(lo), "v"(hi)); return r; }
;     __device__ __forceinline__ void operator()(const f32x4 (&acc)[2][2][4][2], const Unit& u, int wr, int wc, int fr, int fq) const {
; #pragma unroll
;         for (int ai = 0; ai < 2; ++ai)
; #pragma unroll
;             for (int m = 0; m < 4; ++m) {
;                 const int row = u.pm * BM + ai * HALF + wr * 64 + m * 16 + fr;
; #pragma unroll
;                 for (int bj = 0; bj < 2; ++bj) {
;                     const int col = u.pn * BM + bj * HALF + wc * 32 + fq * 8;
;                     const u32x4 zg = *(const u32x4*)(Z + (size_t)row * NZ + ZGB + col);
;                     const f32x4 v0 = acc[ai][bj][m][0], v1 = acc[ai][bj][m][1];
;                     u32x4 w;
;                     w.x = cvt_pk_bf16(v0[0] * sigmoidf_(bflo(zg.x)), v0[1] * sigmoidf_(bfhi(zg.x)));
;                     w.y = cvt_pk_bf16(v0[2] * sigmoidf_(bflo(zg.y)), v0[3] * sigmoidf_(bfhi(zg.y)));
;                     w.z = cvt_pk_bf16(v1[0] * sigmoidf_(bflo(zg.z)), v1[1] * sigmoidf_(bfhi(zg.z)));
;                     w.w = cvt_pk_bf16(v1[2] * sigmoidf_(bflo(zg.w)), v1[3] * sigmoidf_(bfhi(zg.w)));
;                     *(u32x4*)(MIX + (size_t)row * DM + col) = w;
;                     asm volatile("" ::: "memory");
;                 }
;             }
.LBB0_931:
	v_mul_lo_u32 v0, v156, s16
	v_lshl_add_u32 v0, v158, 1, v0
	v_add_u32_e32 v0, 0x3a00, v0
	global_load_dwordx4 v[164:167], v0, s[2:3]
	global_load_dwordx4 v[176:179], v0, s[2:3] offset:256
	v_add_u32_e32 v132, 0x42000, v0
	global_load_dwordx4 v[180:183], v132, s[2:3]
	v_add_u32_e32 v132, 0x42000, v0
	global_load_dwordx4 v[184:187], v132, s[2:3] offset:256
	v_add_u32_e32 v132, 0x84000, v0
	global_load_dwordx4 v[188:191], v132, s[2:3]
	v_add_u32_e32 v132, 0x84000, v0
	global_load_dwordx4 v[192:195], v132, s[2:3] offset:256
	v_add_u32_e32 v132, 0xc6000, v0
	global_load_dwordx4 v[196:199], v132, s[2:3]
	v_add_u32_e32 v132, 0xc6000, v0
	global_load_dwordx4 v[200:203], v132, s[2:3] offset:256
	v_add_u32_e32 v132, 0x210000, v0
	global_load_dwordx4 v[204:207], v132, s[2:3]
	v_add_u32_e32 v132, 0x210000, v0
	global_load_dwordx4 v[208:211], v132, s[2:3] offset:256
	v_add_u32_e32 v132, 0x252000, v0
	global_load_dwordx4 v[212:215], v132, s[2:3]
	v_add_u32_e32 v132, 0x252000, v0
	global_load_dwordx4 v[216:219], v132, s[2:3] offset:256
	v_add_u32_e32 v132, 0x294000, v0
	global_load_dwordx4 v[220:223], v132, s[2:3]
	v_add_u32_e32 v132, 0x294000, v0
	global_load_dwordx4 v[224:227], v132, s[2:3] offset:256
	v_add_u32_e32 v0, 0x2d6000, v0
	v_mov_b64_e32 v[134:135], s[2:3]
	v_mad_i64_i32 v[2:3], s[4:5], v156, s16, v[134:135]
	v_ashrrev_i32_e32 v159, 31, v158
	v_lshl_add_u64 v[160:161], v[2:3], 0, s[46:47]
	v_lshlrev_b64 v[2:3], 1, v[158:159]
	v_lshl_add_u64 v[132:133], v[160:161], 0, v[2:3]
	v_ashrrev_i32_e32 v157, 31, v156
	v_or_b32_e32 v132, 0x80, v158
	v_lshlrev_b64 v[158:159], 11, v[156:157]
	v_lshl_add_u64 v[158:159], s[34:35], 0, v[158:159]
	v_ashrrev_i32_e32 v133, 31, v132
	v_lshl_add_u64 v[158:159], v[158:159], 0, v[2:3]
	v_lshlrev_b64 v[132:133], 1, v[132:133]
	v_lshl_add_u64 v[160:161], v[160:161], 0, v[132:133]
	s_and_b64 vcc, exec, s[38:39]
	s_waitcnt vmcnt(13)
	v_lshlrev_b32_e32 v163, 16, v167
	v_and_b32_e32 v167, 0xffff0000, v167
	v_lshlrev_b32_e32 v1, 16, v164
	v_and_b32_e32 v164, 0xffff0000, v164
	v_lshlrev_b32_e32 v157, 16, v165
	v_and_b32_e32 v165, 0xffff0000, v165
	v_lshlrev_b32_e32 v162, 16, v166
	v_and_b32_e32 v166, 0xffff0000, v166
	v_mul_f32_e32 v167, 0xbfb8aa3b, v167
	v_mul_f32_e32 v1, 0xbfb8aa3b, v1
	v_mul_f32_e32 v164, 0xbfb8aa3b, v164
	v_mul_f32_e32 v157, 0xbfb8aa3b, v157
	v_mul_f32_e32 v165, 0xbfb8aa3b, v165
	v_mul_f32_e32 v162, 0xbfb8aa3b, v162
	v_mul_f32_e32 v166, 0xbfb8aa3b, v166
	v_mul_f32_e32 v163, 0xbfb8aa3b, v163
	v_exp_f32_e32 v167, v167
	v_exp_f32_e32 v1, v1
	v_exp_f32_e32 v164, v164
	v_exp_f32_e32 v157, v157
	v_exp_f32_e32 v165, v165
	v_exp_f32_e32 v162, v162
	v_exp_f32_e32 v166, v166
	v_exp_f32_e32 v163, v163
	v_add_f32_e32 v167, 1.0, v167
	v_add_f32_e32 v1, 1.0, v1
	v_add_f32_e32 v164, 1.0, v164
	v_add_f32_e32 v157, 1.0, v157
	v_add_f32_e32 v165, 1.0, v165
	v_add_f32_e32 v162, 1.0, v162
	v_add_f32_e32 v166, 1.0, v166
	v_add_f32_e32 v163, 1.0, v163
	v_rcp_f32_e32 v167, v167
	v_rcp_f32_e32 v1, v1
	v_rcp_f32_e32 v164, v164
	v_rcp_f32_e32 v157, v157
	v_rcp_f32_e32 v165, v165
	v_rcp_f32_e32 v162, v162
	v_rcp_f32_e32 v166, v166
	v_rcp_f32_e32 v163, v163
	v_mul_f32_e32 v127, v127, v167
	v_mul_f32_e32 v1, v128, v1
	v_mul_f32_e32 v128, v129, v164
	v_mul_f32_e32 v129, v130, v157
	v_mul_f32_e32 v130, v131, v165
	v_mul_f32_e32 v131, v124, v162
	v_mul_f32_e32 v164, v125, v166
	v_mul_f32_e32 v165, v126, v163
	v_cvt_pk_bf16_f32 v124, v1, v128
	v_cvt_pk_bf16_f32 v125, v129, v130
	v_cvt_pk_bf16_f32 v126, v131, v164
	v_cvt_pk_bf16_f32 v127, v165, v127
	global_store_dwordx4 v[158:159], v[124:127], off
	global_load_dwordx4 v[164:167], v0, s[2:3]
	v_or_b32_e32 v128, 16, v156
	v_mad_i64_i32 v[130:131], s[4:5], v128, s16, v[134:135]
	v_lshl_add_u64 v[130:131], v[130:131], 0, s[46:47]
	v_lshl_add_u64 v[136:137], v[130:131], 0, v[2:3]
	s_waitcnt vmcnt(14)
	v_lshlrev_b32_e32 v139, 16, v179
	v_and_b32_e32 v179, 0xffff0000, v179
	v_lshlrev_b32_e32 v1, 16, v176
	v_and_b32_e32 v176, 0xffff0000, v176
	v_lshlrev_b32_e32 v129, 16, v177
	v_and_b32_e32 v177, 0xffff0000, v177
	v_lshlrev_b32_e32 v138, 16, v178
	v_and_b32_e32 v178, 0xffff0000, v178
	v_mul_f32_e32 v179, 0xbfb8aa3b, v179
	v_mul_f32_e32 v1, 0xbfb8aa3b, v1
	v_mul_f32_e32 v176, 0xbfb8aa3b, v176
	v_mul_f32_e32 v129, 0xbfb8aa3b, v129
	v_mul_f32_e32 v177, 0xbfb8aa3b, v177
	v_mul_f32_e32 v138, 0xbfb8aa3b, v138
	v_mul_f32_e32 v178, 0xbfb8aa3b, v178
	v_mul_f32_e32 v139, 0xbfb8aa3b, v139
	v_exp_f32_e32 v179, v179
	v_exp_f32_e32 v1, v1
	v_exp_f32_e32 v176, v176
	v_exp_f32_e32 v129, v129
	v_exp_f32_e32 v177, v177
	v_exp_f32_e32 v138, v138
	v_exp_f32_e32 v178, v178
	v_exp_f32_e32 v139, v139
	v_add_f32_e32 v179, 1.0, v179
	v_add_f32_e32 v1, 1.0, v1
	v_add_f32_e32 v176, 1.0, v176
	v_add_f32_e32 v129, 1.0, v129
	v_add_f32_e32 v177, 1.0, v177
	v_add_f32_e32 v138, 1.0, v138
	v_add_f32_e32 v178, 1.0, v178
	v_add_f32_e32 v139, 1.0, v139
	v_rcp_f32_e32 v179, v179
	v_rcp_f32_e32 v1, v1
	v_rcp_f32_e32 v176, v176
	v_rcp_f32_e32 v129, v129
	v_rcp_f32_e32 v177, v177
	v_rcp_f32_e32 v138, v138
	v_rcp_f32_e32 v178, v178
	v_rcp_f32_e32 v139, v139
	v_mul_f32_e32 v119, v119, v179
	v_mul_f32_e32 v1, v120, v1
	v_mul_f32_e32 v120, v121, v176
	v_mul_f32_e32 v121, v122, v129
	v_mul_f32_e32 v122, v123, v177
	v_mul_f32_e32 v123, v116, v138
	v_mul_f32_e32 v176, v117, v178
	v_mul_f32_e32 v177, v118, v139
	v_cvt_pk_bf16_f32 v116, v1, v120
	v_cvt_pk_bf16_f32 v117, v121, v122
	v_cvt_pk_bf16_f32 v118, v123, v176
	v_cvt_pk_bf16_f32 v119, v177, v119
	global_store_dwordx4 v[158:159], v[116:119], off offset:256
	global_load_dwordx4 v[176:179], v0, s[2:3] offset:256
	v_ashrrev_i32_e32 v129, 31, v128
	v_lshlrev_b64 v[120:121], 11, v[128:129]
	v_lshl_add_u64 v[120:121], s[34:35], 0, v[120:121]
	v_lshl_add_u64 v[120:121], v[120:121], 0, v[2:3]
	v_lshl_add_u64 v[122:123], v[130:131], 0, v[132:133]
	s_waitcnt vmcnt(15)
; __device__ __forceinline__ float sigmoidf_(float x) { return __builtin_amdgcn_rcpf(1.0f + __builtin_amdgcn_exp2f(-x * LOG2E)); }
; __device__ __forceinline__ unsigned cvt_pk_bf16(float lo, float hi) { unsigned r; asm volatile("v_cvt_pk_bf16_f32 %0, %1, %2" : "=v"(r) : "v"(lo), "v"(hi)); return r; }
;     __device__ __forceinline__ void operator()(const f32x4 (&acc)[2][2][4][2], const Unit& u, int wr, int wc, int fr, int fq) const {
; #pragma unroll
;         for (int ai = 0; ai < 2; ++ai)
; #pragma unroll
;             for (int m = 0; m < 4; ++m) {
;                 const int row = u.pm * BM + ai * HALF + wr * 64 + m * 16 + fr;
; #pragma unroll
;                 for (int bj = 0; bj < 2; ++bj) {
;                     const int col = u.pn * BM + bj * HALF + wc * 32 + fq * 8;
;                     const u32x4 zg = *(const u32x4*)(Z + (size_t)row * NZ + ZGB + col);
;                     const f32x4 v0 = acc[ai][bj][m][0], v1 = acc[ai][bj][m][1];
;                     u32x4 w;
;                     w.x = cvt_pk_bf16(v0[0] * sigmoidf_(bflo(zg.x)), v0[1] * sigmoidf_(bfhi(zg.x)));
;                     w.y = cvt_pk_bf16(v0[2] * sigmoidf_(bflo(zg.y)), v0[3] * sigmoidf_(bfhi(zg.y)));
;                     w.z = cvt_pk_bf16(v1[0] * sigmoidf_(bflo(zg.z)), v1[1] * sigmoidf_(bfhi(zg.z)));
;                     w.w = cvt_pk_bf16(v1[2] * sigmoidf_(bflo(zg.w)), v1[3] * sigmoidf_(bfhi(zg.w)));
;                     *(u32x4*)(MIX + (size_t)row * DM + col) = w;
;                     asm volatile("" ::: "memory");
;                 }
;             }
	v_lshlrev_b32_e32 v126, 16, v183
	v_and_b32_e32 v183, 0xffff0000, v183
	v_lshlrev_b32_e32 v1, 16, v180
	v_and_b32_e32 v180, 0xffff0000, v180
	v_lshlrev_b32_e32 v124, 16, v181
	v_and_b32_e32 v181, 0xffff0000, v181
	v_lshlrev_b32_e32 v125, 16, v182
	v_and_b32_e32 v182, 0xffff0000, v182
	v_mul_f32_e32 v183, 0xbfb8aa3b, v183
	v_mul_f32_e32 v1, 0xbfb8aa3b, v1
	v_mul_f32_e32 v180, 0xbfb8aa3b, v180
	v_mul_f32_e32 v124, 0xbfb8aa3b, v124
	v_mul_f32_e32 v181, 0xbfb8aa3b, v181
	v_mul_f32_e32 v125, 0xbfb8aa3b, v125
	v_mul_f32_e32 v182, 0xbfb8aa3b, v182
	v_mul_f32_e32 v126, 0xbfb8aa3b, v126
	v_exp_f32_e32 v183, v183
	v_exp_f32_e32 v1, v1
	v_exp_f32_e32 v180, v180
	v_exp_f32_e32 v124, v124
	v_exp_f32_e32 v181, v181
	v_exp_f32_e32 v125, v125
	v_exp_f32_e32 v182, v182
	v_exp_f32_e32 v126, v126
	v_add_f32_e32 v183, 1.0, v183
	v_add_f32_e32 v1, 1.0, v1
	v_add_f32_e32 v180, 1.0, v180
	v_add_f32_e32 v124, 1.0, v124
	v_add_f32_e32 v181, 1.0, v181
	v_add_f32_e32 v125, 1.0, v125
	v_add_f32_e32 v182, 1.0, v182
	v_add_f32_e32 v126, 1.0, v126
	v_rcp_f32_e32 v183, v183
	v_rcp_f32_e32 v1, v1
	v_rcp_f32_e32 v180, v180
	v_rcp_f32_e32 v124, v124
	v_rcp_f32_e32 v181, v181
	v_rcp_f32_e32 v125, v125
	v_rcp_f32_e32 v182, v182
	v_rcp_f32_e32 v126, v126
	v_mul_f32_e32 v111, v111, v183
	v_mul_f32_e32 v1, v112, v1
	v_mul_f32_e32 v112, v113, v180
	v_mul_f32_e32 v113, v114, v124
	v_mul_f32_e32 v114, v115, v181
	v_mul_f32_e32 v115, v108, v125
	v_mul_f32_e32 v180, v109, v182
	v_mul_f32_e32 v181, v110, v126
	v_cvt_pk_bf16_f32 v108, v1, v112
	v_cvt_pk_bf16_f32 v109, v113, v114
	v_cvt_pk_bf16_f32 v110, v115, v180
	v_cvt_pk_bf16_f32 v111, v181, v111
	global_store_dwordx4 v[120:121], v[108:111], off
	v_or_b32_e32 v112, 32, v156
	v_mad_i64_i32 v[114:115], s[4:5], v112, s16, v[134:135]
	v_lshl_add_u64 v[114:115], v[114:115], 0, s[46:47]
	v_lshl_add_u64 v[116:117], v[114:115], 0, v[2:3]
	s_waitcnt vmcnt(15)
	v_lshlrev_b32_e32 v119, 16, v187
	v_and_b32_e32 v187, 0xffff0000, v187
	v_lshlrev_b32_e32 v1, 16, v184
	v_and_b32_e32 v184, 0xffff0000, v184
	v_lshlrev_b32_e32 v113, 16, v185
	v_and_b32_e32 v185, 0xffff0000, v185
	v_lshlrev_b32_e32 v118, 16, v186
	v_and_b32_e32 v186, 0xffff0000, v186
	v_mul_f32_e32 v187, 0xbfb8aa3b, v187
	v_mul_f32_e32 v1, 0xbfb8aa3b, v1
	v_mul_f32_e32 v184, 0xbfb8aa3b, v184
	v_mul_f32_e32 v113, 0xbfb8aa3b, v113
	v_mul_f32_e32 v185, 0xbfb8aa3b, v185
	v_mul_f32_e32 v118, 0xbfb8aa3b, v118
	v_mul_f32_e32 v186, 0xbfb8aa3b, v186
	v_mul_f32_e32 v119, 0xbfb8aa3b, v119
	v_exp_f32_e32 v187, v187
	v_exp_f32_e32 v1, v1
	v_exp_f32_e32 v184, v184
	v_exp_f32_e32 v113, v113
	v_exp_f32_e32 v185, v185
	v_exp_f32_e32 v118, v118
	v_exp_f32_e32 v186, v186
	v_exp_f32_e32 v119, v119
	v_add_f32_e32 v187, 1.0, v187
	v_add_f32_e32 v1, 1.0, v1
	v_add_f32_e32 v184, 1.0, v184
	v_add_f32_e32 v113, 1.0, v113
	v_add_f32_e32 v185, 1.0, v185
	v_add_f32_e32 v118, 1.0, v118
	v_add_f32_e32 v186, 1.0, v186
	v_add_f32_e32 v119, 1.0, v119
	v_rcp_f32_e32 v187, v187
	v_rcp_f32_e32 v1, v1
	v_rcp_f32_e32 v184, v184
	v_rcp_f32_e32 v113, v113
	v_rcp_f32_e32 v185, v185
	v_rcp_f32_e32 v118, v118
	v_rcp_f32_e32 v186, v186
	v_rcp_f32_e32 v119, v119
	v_mul_f32_e32 v103, v103, v187
	v_mul_f32_e32 v1, v104, v1
	v_mul_f32_e32 v104, v105, v184
	v_mul_f32_e32 v105, v106, v113
	v_mul_f32_e32 v106, v107, v185
	v_mul_f32_e32 v107, v100, v118
	v_mul_f32_e32 v184, v101, v186
	v_mul_f32_e32 v185, v102, v119
	v_cvt_pk_bf16_f32 v100, v1, v104
	v_cvt_pk_bf16_f32 v101, v105, v106
	v_cvt_pk_bf16_f32 v102, v107, v184
	v_cvt_pk_bf16_f32 v103, v185, v103
	global_store_dwordx4 v[120:121], v[100:103], off offset:256
	v_ashrrev_i32_e32 v113, 31, v112
	v_lshlrev_b64 v[104:105], 11, v[112:113]
	v_lshl_add_u64 v[104:105], s[34:35], 0, v[104:105]
	v_lshl_add_u64 v[104:105], v[104:105], 0, v[2:3]
	v_lshl_add_u64 v[106:107], v[114:115], 0, v[132:133]
	s_waitcnt vmcnt(15)
	v_lshlrev_b32_e32 v110, 16, v191
	v_and_b32_e32 v191, 0xffff0000, v191
	v_lshlrev_b32_e32 v1, 16, v188
	v_and_b32_e32 v188, 0xffff0000, v188
	v_lshlrev_b32_e32 v108, 16, v189
	v_and_b32_e32 v189, 0xffff0000, v189
	v_lshlrev_b32_e32 v109, 16, v190
	v_and_b32_e32 v190, 0xffff0000, v190
	v_mul_f32_e32 v191, 0xbfb8aa3b, v191
	v_mul_f32_e32 v1, 0xbfb8aa3b, v1
	v_mul_f32_e32 v188, 0xbfb8aa3b, v188
	v_mul_f32_e32 v108, 0xbfb8aa3b, v108
	v_mul_f32_e32 v189, 0xbfb8aa3b, v189
	v_mul_f32_e32 v109, 0xbfb8aa3b, v109
	v_mul_f32_e32 v190, 0xbfb8aa3b, v190
	v_mul_f32_e32 v110, 0xbfb8aa3b, v110
	v_exp_f32_e32 v191, v191
	v_exp_f32_e32 v1, v1
	v_exp_f32_e32 v188, v188
	v_exp_f32_e32 v108, v108
	v_exp_f32_e32 v189, v189
	v_exp_f32_e32 v109, v109
	v_exp_f32_e32 v190, v190
	v_exp_f32_e32 v110, v110
	v_add_f32_e32 v191, 1.0, v191
	v_add_f32_e32 v1, 1.0, v1
	v_add_f32_e32 v188, 1.0, v188
	v_add_f32_e32 v108, 1.0, v108
	v_add_f32_e32 v189, 1.0, v189
	v_add_f32_e32 v109, 1.0, v109
	v_add_f32_e32 v190, 1.0, v190
	v_add_f32_e32 v110, 1.0, v110
	v_rcp_f32_e32 v191, v191
	v_rcp_f32_e32 v1, v1
	v_rcp_f32_e32 v188, v188
	v_rcp_f32_e32 v108, v108
	v_rcp_f32_e32 v189, v189
	v_rcp_f32_e32 v109, v109
	v_rcp_f32_e32 v190, v190
	v_rcp_f32_e32 v110, v110
	v_mul_f32_e32 v95, v95, v191
	v_mul_f32_e32 v1, v96, v1
	v_mul_f32_e32 v96, v97, v188
	v_mul_f32_e32 v97, v98, v108
	v_mul_f32_e32 v98, v99, v189
	v_mul_f32_e32 v99, v92, v109
	v_mul_f32_e32 v188, v93, v190
	v_mul_f32_e32 v189, v94, v110
	v_cvt_pk_bf16_f32 v92, v1, v96
	v_cvt_pk_bf16_f32 v93, v97, v98
	v_cvt_pk_bf16_f32 v94, v99, v188
	v_cvt_pk_bf16_f32 v95, v189, v95
	global_store_dwordx4 v[104:105], v[92:95], off
	v_or_b32_e32 v96, 48, v156
	v_mad_i64_i32 v[98:99], s[4:5], v96, s16, v[134:135]
	v_lshl_add_u64 v[98:99], v[98:99], 0, s[46:47]
	v_lshl_add_u64 v[100:101], v[98:99], 0, v[2:3]
	s_waitcnt vmcnt(15)
; __device__ __forceinline__ float sigmoidf_(float x) { return __builtin_amdgcn_rcpf(1.0f + __builtin_amdgcn_exp2f(-x * LOG2E)); }
; __device__ __forceinline__ unsigned cvt_pk_bf16(float lo, float hi) { unsigned r; asm volatile("v_cvt_pk_bf16_f32 %0, %1, %2" : "=v"(r) : "v"(lo), "v"(hi)); return r; }
;     __device__ __forceinline__ void operator()(const f32x4 (&acc)[2][2][4][2], const Unit& u, int wr, int wc, int fr, int fq) const {
;     ...
;                     const int col = u.pn * BM + bj * HALF + wc * 32 + fq * 8;
;                     const u32x4 zg = *(const u32x4*)(Z + (size_t)row * NZ + ZGB + col);
;                     const f32x4 v0 = acc[ai][bj][m][0], v1 = acc[ai][bj][m][1];
;                     u32x4 w;
;                     w.x = cvt_pk_bf16(v0[0] * sigmoidf_(bflo(zg.x)), v0[1] * sigmoidf_(bfhi(zg.x)));
;                     w.y = cvt_pk_bf16(v0[2] * sigmoidf_(bflo(zg.y)), v0[3] * sigmoidf_(bfhi(zg.y)));
;                     w.z = cvt_pk_bf16(v1[0] * sigmoidf_(bflo(zg.z)), v1[1] * sigmoidf_(bfhi(zg.z)));
;                     w.w = cvt_pk_bf16(v1[2] * sigmoidf_(bflo(zg.w)), v1[3] * sigmoidf_(bfhi(zg.w)));
;                     *(u32x4*)(MIX + (size_t)row * DM + col) = w;
	v_lshlrev_b32_e32 v103, 16, v195
	v_and_b32_e32 v195, 0xffff0000, v195
	v_lshlrev_b32_e32 v1, 16, v192
	v_and_b32_e32 v192, 0xffff0000, v192
	v_lshlrev_b32_e32 v97, 16, v193
	v_and_b32_e32 v193, 0xffff0000, v193
	v_lshlrev_b32_e32 v102, 16, v194
	v_and_b32_e32 v194, 0xffff0000, v194
	v_mul_f32_e32 v195, 0xbfb8aa3b, v195
	v_mul_f32_e32 v1, 0xbfb8aa3b, v1
	v_mul_f32_e32 v192, 0xbfb8aa3b, v192
	v_mul_f32_e32 v97, 0xbfb8aa3b, v97
	v_mul_f32_e32 v193, 0xbfb8aa3b, v193
	v_mul_f32_e32 v102, 0xbfb8aa3b, v102
	v_mul_f32_e32 v194, 0xbfb8aa3b, v194
	v_mul_f32_e32 v103, 0xbfb8aa3b, v103
	v_exp_f32_e32 v195, v195
	v_exp_f32_e32 v1, v1
	v_exp_f32_e32 v192, v192
	v_exp_f32_e32 v97, v97
	v_exp_f32_e32 v193, v193
	v_exp_f32_e32 v102, v102
	v_exp_f32_e32 v194, v194
	v_exp_f32_e32 v103, v103
	v_add_f32_e32 v195, 1.0, v195
	v_add_f32_e32 v1, 1.0, v1
	v_add_f32_e32 v192, 1.0, v192
	v_add_f32_e32 v97, 1.0, v97
	v_add_f32_e32 v193, 1.0, v193
	v_add_f32_e32 v102, 1.0, v102
	v_add_f32_e32 v194, 1.0, v194
	v_add_f32_e32 v103, 1.0, v103
	v_rcp_f32_e32 v195, v195
	v_rcp_f32_e32 v1, v1
	v_rcp_f32_e32 v192, v192
	v_rcp_f32_e32 v97, v97
	v_rcp_f32_e32 v193, v193
	v_rcp_f32_e32 v102, v102
	v_rcp_f32_e32 v194, v194
	v_rcp_f32_e32 v103, v103
	v_mul_f32_e32 v87, v87, v195
	v_mul_f32_e32 v1, v88, v1
	v_mul_f32_e32 v88, v89, v192
	v_mul_f32_e32 v89, v90, v97
	v_mul_f32_e32 v90, v91, v193
	v_mul_f32_e32 v91, v84, v102
	v_mul_f32_e32 v192, v85, v194
	v_mul_f32_e32 v193, v86, v103
	v_cvt_pk_bf16_f32 v84, v1, v88
	v_cvt_pk_bf16_f32 v85, v89, v90
	v_cvt_pk_bf16_f32 v86, v91, v192
	v_cvt_pk_bf16_f32 v87, v193, v87
	global_store_dwordx4 v[104:105], v[84:87], off offset:256
	v_ashrrev_i32_e32 v97, 31, v96
	v_lshlrev_b64 v[88:89], 11, v[96:97]
	v_lshl_add_u64 v[88:89], s[34:35], 0, v[88:89]
	v_lshl_add_u64 v[88:89], v[88:89], 0, v[2:3]
	v_lshl_add_u64 v[90:91], v[98:99], 0, v[132:133]
	s_waitcnt vmcnt(15)
	v_lshlrev_b32_e32 v94, 16, v199
	v_and_b32_e32 v199, 0xffff0000, v199
	v_lshlrev_b32_e32 v1, 16, v196
	v_and_b32_e32 v196, 0xffff0000, v196
	v_lshlrev_b32_e32 v92, 16, v197
	v_and_b32_e32 v197, 0xffff0000, v197
	v_lshlrev_b32_e32 v93, 16, v198
	v_and_b32_e32 v198, 0xffff0000, v198
	v_mul_f32_e32 v199, 0xbfb8aa3b, v199
	v_mul_f32_e32 v1, 0xbfb8aa3b, v1
	v_mul_f32_e32 v196, 0xbfb8aa3b, v196
	v_mul_f32_e32 v92, 0xbfb8aa3b, v92
	v_mul_f32_e32 v197, 0xbfb8aa3b, v197
	v_mul_f32_e32 v93, 0xbfb8aa3b, v93
	v_mul_f32_e32 v198, 0xbfb8aa3b, v198
	v_mul_f32_e32 v94, 0xbfb8aa3b, v94
	v_exp_f32_e32 v199, v199
	v_exp_f32_e32 v1, v1
	v_exp_f32_e32 v196, v196
	v_exp_f32_e32 v92, v92
	v_exp_f32_e32 v197, v197
	v_exp_f32_e32 v93, v93
	v_exp_f32_e32 v198, v198
	v_exp_f32_e32 v94, v94
	v_add_f32_e32 v199, 1.0, v199
	v_add_f32_e32 v1, 1.0, v1
	v_add_f32_e32 v196, 1.0, v196
	v_add_f32_e32 v92, 1.0, v92
	v_add_f32_e32 v197, 1.0, v197
	v_add_f32_e32 v93, 1.0, v93
	v_add_f32_e32 v198, 1.0, v198
	v_add_f32_e32 v94, 1.0, v94
	v_rcp_f32_e32 v199, v199
	v_rcp_f32_e32 v1, v1
	v_rcp_f32_e32 v196, v196
	v_rcp_f32_e32 v92, v92
	v_rcp_f32_e32 v197, v197
	v_rcp_f32_e32 v93, v93
	v_rcp_f32_e32 v198, v198
	v_rcp_f32_e32 v94, v94
	v_mul_f32_e32 v79, v79, v199
	v_mul_f32_e32 v1, v80, v1
	v_mul_f32_e32 v80, v81, v196
	v_mul_f32_e32 v81, v82, v92
	v_mul_f32_e32 v82, v83, v197
	v_mul_f32_e32 v83, v76, v93
	v_mul_f32_e32 v196, v77, v198
	v_mul_f32_e32 v197, v78, v94
	v_cvt_pk_bf16_f32 v76, v1, v80
	v_cvt_pk_bf16_f32 v77, v81, v82
	v_cvt_pk_bf16_f32 v78, v83, v196
	v_cvt_pk_bf16_f32 v79, v197, v79
	global_store_dwordx4 v[88:89], v[76:79], off
	v_add_u32_e32 v80, 0x80, v156
	v_mad_i64_i32 v[82:83], s[4:5], v80, s16, v[134:135]
	v_lshl_add_u64 v[82:83], v[82:83], 0, s[46:47]
	v_lshl_add_u64 v[84:85], v[82:83], 0, v[2:3]
	s_waitcnt vmcnt(15)
	v_lshlrev_b32_e32 v87, 16, v203
	v_and_b32_e32 v203, 0xffff0000, v203
	v_lshlrev_b32_e32 v1, 16, v200
	v_and_b32_e32 v200, 0xffff0000, v200
	v_lshlrev_b32_e32 v81, 16, v201
	v_and_b32_e32 v201, 0xffff0000, v201
	v_lshlrev_b32_e32 v86, 16, v202
	v_and_b32_e32 v202, 0xffff0000, v202
	v_mul_f32_e32 v203, 0xbfb8aa3b, v203
	v_mul_f32_e32 v1, 0xbfb8aa3b, v1
	v_mul_f32_e32 v200, 0xbfb8aa3b, v200
	v_mul_f32_e32 v81, 0xbfb8aa3b, v81
	v_mul_f32_e32 v201, 0xbfb8aa3b, v201
	v_mul_f32_e32 v86, 0xbfb8aa3b, v86
	v_mul_f32_e32 v202, 0xbfb8aa3b, v202
	v_mul_f32_e32 v87, 0xbfb8aa3b, v87
	v_exp_f32_e32 v203, v203
	v_exp_f32_e32 v1, v1
	v_exp_f32_e32 v200, v200
	v_exp_f32_e32 v81, v81
	v_exp_f32_e32 v201, v201
	v_exp_f32_e32 v86, v86
	v_exp_f32_e32 v202, v202
	v_exp_f32_e32 v87, v87
	v_add_f32_e32 v203, 1.0, v203
	v_add_f32_e32 v1, 1.0, v1
	v_add_f32_e32 v200, 1.0, v200
	v_add_f32_e32 v81, 1.0, v81
	v_add_f32_e32 v201, 1.0, v201
	v_add_f32_e32 v86, 1.0, v86
	v_add_f32_e32 v202, 1.0, v202
	v_add_f32_e32 v87, 1.0, v87
	v_rcp_f32_e32 v203, v203
	v_rcp_f32_e32 v1, v1
	v_rcp_f32_e32 v200, v200
	v_rcp_f32_e32 v81, v81
	v_rcp_f32_e32 v201, v201
	v_rcp_f32_e32 v86, v86
	v_rcp_f32_e32 v202, v202
	v_rcp_f32_e32 v87, v87
	v_mul_f32_e32 v71, v71, v203
	v_mul_f32_e32 v1, v72, v1
	v_mul_f32_e32 v72, v73, v200
	v_mul_f32_e32 v73, v74, v81
	v_mul_f32_e32 v74, v75, v201
	v_mul_f32_e32 v75, v68, v86
	v_mul_f32_e32 v200, v69, v202
	v_mul_f32_e32 v201, v70, v87
	v_cvt_pk_bf16_f32 v68, v1, v72
	v_cvt_pk_bf16_f32 v69, v73, v74
	v_cvt_pk_bf16_f32 v70, v75, v200
	v_cvt_pk_bf16_f32 v71, v201, v71
	global_store_dwordx4 v[88:89], v[68:71], off offset:256
	v_ashrrev_i32_e32 v81, 31, v80
	v_lshlrev_b64 v[72:73], 11, v[80:81]
	v_lshl_add_u64 v[72:73], s[34:35], 0, v[72:73]
	v_lshl_add_u64 v[72:73], v[72:73], 0, v[2:3]
	v_lshl_add_u64 v[74:75], v[82:83], 0, v[132:133]
	s_waitcnt vmcnt(15)
; __device__ __forceinline__ float sigmoidf_(float x) { return __builtin_amdgcn_rcpf(1.0f + __builtin_amdgcn_exp2f(-x * LOG2E)); }
; __device__ __forceinline__ unsigned cvt_pk_bf16(float lo, float hi) { unsigned r; asm volatile("v_cvt_pk_bf16_f32 %0, %1, %2" : "=v"(r) : "v"(lo), "v"(hi)); return r; }
;     __device__ __forceinline__ void operator()(const f32x4 (&acc)[2][2][4][2], const Unit& u, int wr, int wc, int fr, int fq) const {
;     ...
;                     const int col = u.pn * BM + bj * HALF + wc * 32 + fq * 8;
;                     const u32x4 zg = *(const u32x4*)(Z + (size_t)row * NZ + ZGB + col);
;                     const f32x4 v0 = acc[ai][bj][m][0], v1 = acc[ai][bj][m][1];
;                     u32x4 w;
;                     w.x = cvt_pk_bf16(v0[0] * sigmoidf_(bflo(zg.x)), v0[1] * sigmoidf_(bfhi(zg.x)));
;                     w.y = cvt_pk_bf16(v0[2] * sigmoidf_(bflo(zg.y)), v0[3] * sigmoidf_(bfhi(zg.y)));
;                     w.z = cvt_pk_bf16(v1[0] * sigmoidf_(bflo(zg.z)), v1[1] * sigmoidf_(bfhi(zg.z)));
;                     w.w = cvt_pk_bf16(v1[2] * sigmoidf_(bflo(zg.w)), v1[3] * sigmoidf_(bfhi(zg.w)));
;                     *(u32x4*)(MIX + (size_t)row * DM + col) = w;
	v_lshlrev_b32_e32 v78, 16, v207
	v_and_b32_e32 v207, 0xffff0000, v207
	v_lshlrev_b32_e32 v1, 16, v204
	v_and_b32_e32 v204, 0xffff0000, v204
	v_lshlrev_b32_e32 v76, 16, v205
	v_and_b32_e32 v205, 0xffff0000, v205
	v_lshlrev_b32_e32 v77, 16, v206
	v_and_b32_e32 v206, 0xffff0000, v206
	v_mul_f32_e32 v207, 0xbfb8aa3b, v207
	v_mul_f32_e32 v1, 0xbfb8aa3b, v1
	v_mul_f32_e32 v204, 0xbfb8aa3b, v204
	v_mul_f32_e32 v76, 0xbfb8aa3b, v76
	v_mul_f32_e32 v205, 0xbfb8aa3b, v205
	v_mul_f32_e32 v77, 0xbfb8aa3b, v77
	v_mul_f32_e32 v206, 0xbfb8aa3b, v206
	v_mul_f32_e32 v78, 0xbfb8aa3b, v78
	v_exp_f32_e32 v207, v207
	v_exp_f32_e32 v1, v1
	v_exp_f32_e32 v204, v204
	v_exp_f32_e32 v76, v76
	v_exp_f32_e32 v205, v205
	v_exp_f32_e32 v77, v77
	v_exp_f32_e32 v206, v206
	v_exp_f32_e32 v78, v78
	v_add_f32_e32 v207, 1.0, v207
	v_add_f32_e32 v1, 1.0, v1
	v_add_f32_e32 v204, 1.0, v204
	v_add_f32_e32 v76, 1.0, v76
	v_add_f32_e32 v205, 1.0, v205
	v_add_f32_e32 v77, 1.0, v77
	v_add_f32_e32 v206, 1.0, v206
	v_add_f32_e32 v78, 1.0, v78
	v_rcp_f32_e32 v207, v207
	v_rcp_f32_e32 v1, v1
	v_rcp_f32_e32 v204, v204
	v_rcp_f32_e32 v76, v76
	v_rcp_f32_e32 v205, v205
	v_rcp_f32_e32 v77, v77
	v_rcp_f32_e32 v206, v206
	v_rcp_f32_e32 v78, v78
	v_mul_f32_e32 v63, v63, v207
	v_mul_f32_e32 v1, v64, v1
	v_mul_f32_e32 v64, v65, v204
	v_mul_f32_e32 v65, v66, v76
	v_mul_f32_e32 v66, v67, v205
	v_mul_f32_e32 v67, v60, v77
	v_mul_f32_e32 v204, v61, v206
	v_mul_f32_e32 v205, v62, v78
	v_cvt_pk_bf16_f32 v60, v1, v64
	v_cvt_pk_bf16_f32 v61, v65, v66
	v_cvt_pk_bf16_f32 v62, v67, v204
	v_cvt_pk_bf16_f32 v63, v205, v63
	global_store_dwordx4 v[72:73], v[60:63], off
	v_add_u32_e32 v64, 0x90, v156
	v_mad_i64_i32 v[66:67], s[4:5], v64, s16, v[134:135]
	v_lshl_add_u64 v[66:67], v[66:67], 0, s[46:47]
	v_lshl_add_u64 v[68:69], v[66:67], 0, v[2:3]
	s_waitcnt vmcnt(15)
	v_lshlrev_b32_e32 v71, 16, v211
	v_and_b32_e32 v211, 0xffff0000, v211
	v_lshlrev_b32_e32 v1, 16, v208
	v_and_b32_e32 v208, 0xffff0000, v208
	v_lshlrev_b32_e32 v65, 16, v209
	v_and_b32_e32 v209, 0xffff0000, v209
	v_lshlrev_b32_e32 v70, 16, v210
	v_and_b32_e32 v210, 0xffff0000, v210
	v_mul_f32_e32 v211, 0xbfb8aa3b, v211
	v_mul_f32_e32 v1, 0xbfb8aa3b, v1
	v_mul_f32_e32 v208, 0xbfb8aa3b, v208
	v_mul_f32_e32 v65, 0xbfb8aa3b, v65
	v_mul_f32_e32 v209, 0xbfb8aa3b, v209
	v_mul_f32_e32 v70, 0xbfb8aa3b, v70
	v_mul_f32_e32 v210, 0xbfb8aa3b, v210
	v_mul_f32_e32 v71, 0xbfb8aa3b, v71
	v_exp_f32_e32 v211, v211
	v_exp_f32_e32 v1, v1
	v_exp_f32_e32 v208, v208
	v_exp_f32_e32 v65, v65
	v_exp_f32_e32 v209, v209
	v_exp_f32_e32 v70, v70
	v_exp_f32_e32 v210, v210
	v_exp_f32_e32 v71, v71
	v_add_f32_e32 v211, 1.0, v211
	v_add_f32_e32 v1, 1.0, v1
	v_add_f32_e32 v208, 1.0, v208
	v_add_f32_e32 v65, 1.0, v65
	v_add_f32_e32 v209, 1.0, v209
	v_add_f32_e32 v70, 1.0, v70
	v_add_f32_e32 v210, 1.0, v210
	v_add_f32_e32 v71, 1.0, v71
	v_rcp_f32_e32 v211, v211
	v_rcp_f32_e32 v1, v1
	v_rcp_f32_e32 v208, v208
	v_rcp_f32_e32 v65, v65
	v_rcp_f32_e32 v209, v209
	v_rcp_f32_e32 v70, v70
	v_rcp_f32_e32 v210, v210
	v_rcp_f32_e32 v71, v71
	v_mul_f32_e32 v55, v55, v211
	v_mul_f32_e32 v1, v56, v1
	v_mul_f32_e32 v56, v57, v208
	v_mul_f32_e32 v57, v58, v65
	v_mul_f32_e32 v58, v59, v209
	v_mul_f32_e32 v59, v52, v70
	v_mul_f32_e32 v208, v53, v210
	v_mul_f32_e32 v209, v54, v71
	v_cvt_pk_bf16_f32 v52, v1, v56
	v_cvt_pk_bf16_f32 v53, v57, v58
	v_cvt_pk_bf16_f32 v54, v59, v208
	v_cvt_pk_bf16_f32 v55, v209, v55
	global_store_dwordx4 v[72:73], v[52:55], off offset:256
	v_ashrrev_i32_e32 v65, 31, v64
	v_lshlrev_b64 v[56:57], 11, v[64:65]
	v_lshl_add_u64 v[56:57], s[34:35], 0, v[56:57]
	v_lshl_add_u64 v[56:57], v[56:57], 0, v[2:3]
	v_lshl_add_u64 v[58:59], v[66:67], 0, v[132:133]
	s_waitcnt vmcnt(15)
	v_lshlrev_b32_e32 v62, 16, v215
	v_and_b32_e32 v215, 0xffff0000, v215
	v_lshlrev_b32_e32 v1, 16, v212
	v_and_b32_e32 v212, 0xffff0000, v212
	v_lshlrev_b32_e32 v60, 16, v213
	v_and_b32_e32 v213, 0xffff0000, v213
	v_lshlrev_b32_e32 v61, 16, v214
	v_and_b32_e32 v214, 0xffff0000, v214
	v_mul_f32_e32 v215, 0xbfb8aa3b, v215
	v_mul_f32_e32 v1, 0xbfb8aa3b, v1
	v_mul_f32_e32 v212, 0xbfb8aa3b, v212
	v_mul_f32_e32 v60, 0xbfb8aa3b, v60
	v_mul_f32_e32 v213, 0xbfb8aa3b, v213
	v_mul_f32_e32 v61, 0xbfb8aa3b, v61
	v_mul_f32_e32 v214, 0xbfb8aa3b, v214
	v_mul_f32_e32 v62, 0xbfb8aa3b, v62
	v_exp_f32_e32 v215, v215
	v_exp_f32_e32 v1, v1
	v_exp_f32_e32 v212, v212
	v_exp_f32_e32 v60, v60
	v_exp_f32_e32 v213, v213
	v_exp_f32_e32 v61, v61
	v_exp_f32_e32 v214, v214
	v_exp_f32_e32 v62, v62
	v_add_f32_e32 v215, 1.0, v215
	v_add_f32_e32 v1, 1.0, v1
	v_add_f32_e32 v212, 1.0, v212
	v_add_f32_e32 v60, 1.0, v60
	v_add_f32_e32 v213, 1.0, v213
	v_add_f32_e32 v61, 1.0, v61
	v_add_f32_e32 v214, 1.0, v214
	v_add_f32_e32 v62, 1.0, v62
	v_rcp_f32_e32 v215, v215
	v_rcp_f32_e32 v1, v1
	v_rcp_f32_e32 v212, v212
	v_rcp_f32_e32 v60, v60
	v_rcp_f32_e32 v213, v213
	v_rcp_f32_e32 v61, v61
	v_rcp_f32_e32 v214, v214
	v_rcp_f32_e32 v62, v62
	v_mul_f32_e32 v47, v47, v215
	v_mul_f32_e32 v1, v48, v1
	v_mul_f32_e32 v48, v49, v212
	v_mul_f32_e32 v49, v50, v60
	v_mul_f32_e32 v50, v51, v213
	v_mul_f32_e32 v51, v44, v61
	v_mul_f32_e32 v212, v45, v214
	v_mul_f32_e32 v213, v46, v62
	v_cvt_pk_bf16_f32 v44, v1, v48
	v_cvt_pk_bf16_f32 v45, v49, v50
	v_cvt_pk_bf16_f32 v46, v51, v212
	v_cvt_pk_bf16_f32 v47, v213, v47
	global_store_dwordx4 v[56:57], v[44:47], off
	v_add_u32_e32 v48, 0xa0, v156
	v_mad_i64_i32 v[50:51], s[4:5], v48, s16, v[134:135]
	v_lshl_add_u64 v[50:51], v[50:51], 0, s[46:47]
	v_lshl_add_u64 v[52:53], v[50:51], 0, v[2:3]
	s_waitcnt vmcnt(15)
; __device__ __forceinline__ float sigmoidf_(float x) { return __builtin_amdgcn_rcpf(1.0f + __builtin_amdgcn_exp2f(-x * LOG2E)); }
; __device__ __forceinline__ unsigned cvt_pk_bf16(float lo, float hi) { unsigned r; asm volatile("v_cvt_pk_bf16_f32 %0, %1, %2" : "=v"(r) : "v"(lo), "v"(hi)); return r; }
;     __device__ __forceinline__ void operator()(const f32x4 (&acc)[2][2][4][2], const Unit& u, int wr, int wc, int fr, int fq) const {
;     ...
;                     const int col = u.pn * BM + bj * HALF + wc * 32 + fq * 8;
;                     const u32x4 zg = *(const u32x4*)(Z + (size_t)row * NZ + ZGB + col);
;                     const f32x4 v0 = acc[ai][bj][m][0], v1 = acc[ai][bj][m][1];
;                     u32x4 w;
;                     w.x = cvt_pk_bf16(v0[0] * sigmoidf_(bflo(zg.x)), v0[1] * sigmoidf_(bfhi(zg.x)));
;                     w.y = cvt_pk_bf16(v0[2] * sigmoidf_(bflo(zg.y)), v0[3] * sigmoidf_(bfhi(zg.y)));
;                     w.z = cvt_pk_bf16(v1[0] * sigmoidf_(bflo(zg.z)), v1[1] * sigmoidf_(bfhi(zg.z)));
;                     w.w = cvt_pk_bf16(v1[2] * sigmoidf_(bflo(zg.w)), v1[3] * sigmoidf_(bfhi(zg.w)));
;                     *(u32x4*)(MIX + (size_t)row * DM + col) = w;
	v_lshlrev_b32_e32 v55, 16, v219
	v_and_b32_e32 v219, 0xffff0000, v219
	v_lshlrev_b32_e32 v1, 16, v216
	v_and_b32_e32 v216, 0xffff0000, v216
	v_lshlrev_b32_e32 v49, 16, v217
	v_and_b32_e32 v217, 0xffff0000, v217
	v_lshlrev_b32_e32 v54, 16, v218
	v_and_b32_e32 v218, 0xffff0000, v218
	v_mul_f32_e32 v219, 0xbfb8aa3b, v219
	v_mul_f32_e32 v1, 0xbfb8aa3b, v1
	v_mul_f32_e32 v216, 0xbfb8aa3b, v216
	v_mul_f32_e32 v49, 0xbfb8aa3b, v49
	v_mul_f32_e32 v217, 0xbfb8aa3b, v217
	v_mul_f32_e32 v54, 0xbfb8aa3b, v54
	v_mul_f32_e32 v218, 0xbfb8aa3b, v218
	v_mul_f32_e32 v55, 0xbfb8aa3b, v55
	v_exp_f32_e32 v219, v219
	v_exp_f32_e32 v1, v1
	v_exp_f32_e32 v216, v216
	v_exp_f32_e32 v49, v49
	v_exp_f32_e32 v217, v217
	v_exp_f32_e32 v54, v54
	v_exp_f32_e32 v218, v218
	v_exp_f32_e32 v55, v55
	v_add_f32_e32 v219, 1.0, v219
	v_add_f32_e32 v1, 1.0, v1
	v_add_f32_e32 v216, 1.0, v216
	v_add_f32_e32 v49, 1.0, v49
	v_add_f32_e32 v217, 1.0, v217
	v_add_f32_e32 v54, 1.0, v54
	v_add_f32_e32 v218, 1.0, v218
	v_add_f32_e32 v55, 1.0, v55
	v_rcp_f32_e32 v219, v219
	v_rcp_f32_e32 v1, v1
	v_rcp_f32_e32 v216, v216
	v_rcp_f32_e32 v49, v49
	v_rcp_f32_e32 v217, v217
	v_rcp_f32_e32 v54, v54
	v_rcp_f32_e32 v218, v218
	v_rcp_f32_e32 v55, v55
	v_mul_f32_e32 v39, v39, v219
	v_mul_f32_e32 v1, v40, v1
	v_mul_f32_e32 v40, v41, v216
	v_mul_f32_e32 v41, v42, v49
	v_mul_f32_e32 v42, v43, v217
	v_mul_f32_e32 v43, v36, v54
	v_mul_f32_e32 v216, v37, v218
	v_mul_f32_e32 v217, v38, v55
	v_cvt_pk_bf16_f32 v36, v1, v40
	v_cvt_pk_bf16_f32 v37, v41, v42
	v_cvt_pk_bf16_f32 v38, v43, v216
	v_cvt_pk_bf16_f32 v39, v217, v39
	global_store_dwordx4 v[56:57], v[36:39], off offset:256
	v_ashrrev_i32_e32 v49, 31, v48
	v_lshlrev_b64 v[40:41], 11, v[48:49]
	v_lshl_add_u64 v[40:41], s[34:35], 0, v[40:41]
	v_lshl_add_u64 v[40:41], v[40:41], 0, v[2:3]
	v_lshl_add_u64 v[42:43], v[50:51], 0, v[132:133]
	s_waitcnt vmcnt(15)
	v_lshlrev_b32_e32 v46, 16, v223
	v_and_b32_e32 v223, 0xffff0000, v223
	v_lshlrev_b32_e32 v1, 16, v220
	v_and_b32_e32 v220, 0xffff0000, v220
	v_lshlrev_b32_e32 v44, 16, v221
	v_and_b32_e32 v221, 0xffff0000, v221
	v_lshlrev_b32_e32 v45, 16, v222
	v_and_b32_e32 v222, 0xffff0000, v222
	v_mul_f32_e32 v223, 0xbfb8aa3b, v223
	v_mul_f32_e32 v1, 0xbfb8aa3b, v1
	v_mul_f32_e32 v220, 0xbfb8aa3b, v220
	v_mul_f32_e32 v44, 0xbfb8aa3b, v44
	v_mul_f32_e32 v221, 0xbfb8aa3b, v221
	v_mul_f32_e32 v45, 0xbfb8aa3b, v45
	v_mul_f32_e32 v222, 0xbfb8aa3b, v222
	v_mul_f32_e32 v46, 0xbfb8aa3b, v46
	v_exp_f32_e32 v223, v223
	v_exp_f32_e32 v1, v1
	v_exp_f32_e32 v220, v220
	v_exp_f32_e32 v44, v44
	v_exp_f32_e32 v221, v221
	v_exp_f32_e32 v45, v45
	v_exp_f32_e32 v222, v222
	v_exp_f32_e32 v46, v46
	v_add_f32_e32 v223, 1.0, v223
	v_add_f32_e32 v1, 1.0, v1
	v_add_f32_e32 v220, 1.0, v220
	v_add_f32_e32 v44, 1.0, v44
	v_add_f32_e32 v221, 1.0, v221
	v_add_f32_e32 v45, 1.0, v45
	v_add_f32_e32 v222, 1.0, v222
	v_add_f32_e32 v46, 1.0, v46
	v_rcp_f32_e32 v223, v223
	v_rcp_f32_e32 v1, v1
	v_rcp_f32_e32 v220, v220
	v_rcp_f32_e32 v44, v44
	v_rcp_f32_e32 v221, v221
	v_rcp_f32_e32 v45, v45
	v_rcp_f32_e32 v222, v222
	v_rcp_f32_e32 v46, v46
	v_mul_f32_e32 v31, v31, v223
	v_mul_f32_e32 v1, v32, v1
	v_mul_f32_e32 v32, v33, v220
	v_mul_f32_e32 v33, v34, v44
	v_mul_f32_e32 v34, v35, v221
	v_mul_f32_e32 v35, v28, v45
	v_mul_f32_e32 v220, v29, v222
	v_mul_f32_e32 v221, v30, v46
	v_cvt_pk_bf16_f32 v28, v1, v32
	v_cvt_pk_bf16_f32 v29, v33, v34
	v_cvt_pk_bf16_f32 v30, v35, v220
	v_cvt_pk_bf16_f32 v31, v221, v31
	global_store_dwordx4 v[40:41], v[28:31], off
	v_add_u32_e32 v32, 0xb0, v156
	v_mad_i64_i32 v[34:35], s[4:5], v32, s16, v[134:135]
	v_lshl_add_u64 v[34:35], v[34:35], 0, s[46:47]
	v_lshl_add_u64 v[36:37], v[34:35], 0, v[2:3]
	s_mov_b64 s[4:5], -1
	s_waitcnt vmcnt(15)
; __device__ __forceinline__ float sigmoidf_(float x) { return __builtin_amdgcn_rcpf(1.0f + __builtin_amdgcn_exp2f(-x * LOG2E)); }
; __device__ __forceinline__ unsigned cvt_pk_bf16(float lo, float hi) { unsigned r; asm volatile("v_cvt_pk_bf16_f32 %0, %1, %2" : "=v"(r) : "v"(lo), "v"(hi)); return r; }
;     __device__ __forceinline__ void operator()(const f32x4 (&acc)[2][2][4][2], const Unit& u, int wr, int wc, int fr, int fq) const {
;     ...
;                     const int col = u.pn * BM + bj * HALF + wc * 32 + fq * 8;
;                     const u32x4 zg = *(const u32x4*)(Z + (size_t)row * NZ + ZGB + col);
;                     const f32x4 v0 = acc[ai][bj][m][0], v1 = acc[ai][bj][m][1];
;                     u32x4 w;
;                     w.x = cvt_pk_bf16(v0[0] * sigmoidf_(bflo(zg.x)), v0[1] * sigmoidf_(bfhi(zg.x)));
;                     w.y = cvt_pk_bf16(v0[2] * sigmoidf_(bflo(zg.y)), v0[3] * sigmoidf_(bfhi(zg.y)));
;                     w.z = cvt_pk_bf16(v1[0] * sigmoidf_(bflo(zg.z)), v1[1] * sigmoidf_(bfhi(zg.z)));
;                     w.w = cvt_pk_bf16(v1[2] * sigmoidf_(bflo(zg.w)), v1[3] * sigmoidf_(bfhi(zg.w)));
;                     *(u32x4*)(MIX + (size_t)row * DM + col) = w;
	v_lshlrev_b32_e32 v39, 16, v227
	v_and_b32_e32 v227, 0xffff0000, v227
	v_lshlrev_b32_e32 v1, 16, v224
	v_and_b32_e32 v224, 0xffff0000, v224
	v_lshlrev_b32_e32 v33, 16, v225
	v_and_b32_e32 v225, 0xffff0000, v225
	v_lshlrev_b32_e32 v38, 16, v226
	v_and_b32_e32 v226, 0xffff0000, v226
	v_mul_f32_e32 v227, 0xbfb8aa3b, v227
	v_mul_f32_e32 v1, 0xbfb8aa3b, v1
	v_mul_f32_e32 v224, 0xbfb8aa3b, v224
	v_mul_f32_e32 v33, 0xbfb8aa3b, v33
	v_mul_f32_e32 v225, 0xbfb8aa3b, v225
	v_mul_f32_e32 v38, 0xbfb8aa3b, v38
	v_mul_f32_e32 v226, 0xbfb8aa3b, v226
	v_mul_f32_e32 v39, 0xbfb8aa3b, v39
	v_exp_f32_e32 v227, v227
	v_exp_f32_e32 v1, v1
	v_exp_f32_e32 v224, v224
	v_exp_f32_e32 v33, v33
	v_exp_f32_e32 v225, v225
	v_exp_f32_e32 v38, v38
	v_exp_f32_e32 v226, v226
	v_exp_f32_e32 v39, v39
	v_add_f32_e32 v227, 1.0, v227
	v_add_f32_e32 v1, 1.0, v1
	v_add_f32_e32 v224, 1.0, v224
	v_add_f32_e32 v33, 1.0, v33
	v_add_f32_e32 v225, 1.0, v225
	v_add_f32_e32 v38, 1.0, v38
	v_add_f32_e32 v226, 1.0, v226
	v_add_f32_e32 v39, 1.0, v39
	v_rcp_f32_e32 v227, v227
	v_rcp_f32_e32 v1, v1
	v_rcp_f32_e32 v224, v224
	v_rcp_f32_e32 v33, v33
	v_rcp_f32_e32 v225, v225
	v_rcp_f32_e32 v38, v38
	v_rcp_f32_e32 v226, v226
	v_rcp_f32_e32 v39, v39
	v_mul_f32_e32 v23, v23, v227
	v_mul_f32_e32 v1, v24, v1
	v_mul_f32_e32 v24, v25, v224
	v_mul_f32_e32 v25, v26, v33
	v_mul_f32_e32 v26, v27, v225
	v_mul_f32_e32 v27, v20, v38
	v_mul_f32_e32 v224, v21, v226
	v_mul_f32_e32 v225, v22, v39
	v_cvt_pk_bf16_f32 v20, v1, v24
	v_cvt_pk_bf16_f32 v21, v25, v26
	v_cvt_pk_bf16_f32 v22, v27, v224
	v_cvt_pk_bf16_f32 v23, v225, v23
	global_store_dwordx4 v[40:41], v[20:23], off offset:256
	v_ashrrev_i32_e32 v33, 31, v32
	v_lshlrev_b64 v[24:25], 11, v[32:33]
	v_lshl_add_u64 v[24:25], s[34:35], 0, v[24:25]
	v_lshl_add_u64 v[24:25], v[24:25], 0, v[2:3]
	v_lshl_add_u64 v[26:27], v[34:35], 0, v[132:133]
	s_waitcnt vmcnt(14)
	v_lshlrev_b32_e32 v28, 16, v167
	v_and_b32_e32 v167, 0xffff0000, v167
	v_lshlrev_b32_e32 v1, 16, v164
	v_and_b32_e32 v2, 0xffff0000, v164
	v_lshlrev_b32_e32 v3, 16, v165
	v_and_b32_e32 v164, 0xffff0000, v165
	v_lshlrev_b32_e32 v165, 16, v166
	v_and_b32_e32 v166, 0xffff0000, v166
	v_mul_f32_e32 v167, 0xbfb8aa3b, v167
	v_mul_f32_e32 v1, 0xbfb8aa3b, v1
	v_mul_f32_e32 v2, 0xbfb8aa3b, v2
	v_mul_f32_e32 v3, 0xbfb8aa3b, v3
	v_mul_f32_e32 v164, 0xbfb8aa3b, v164
	v_mul_f32_e32 v165, 0xbfb8aa3b, v165
	v_mul_f32_e32 v166, 0xbfb8aa3b, v166
	v_mul_f32_e32 v28, 0xbfb8aa3b, v28
	v_exp_f32_e32 v167, v167
	v_exp_f32_e32 v1, v1
	v_exp_f32_e32 v2, v2
	v_exp_f32_e32 v3, v3
	v_exp_f32_e32 v164, v164
	v_exp_f32_e32 v165, v165
	v_exp_f32_e32 v166, v166
	v_exp_f32_e32 v28, v28
	v_add_f32_e32 v167, 1.0, v167
	v_add_f32_e32 v1, 1.0, v1
	v_add_f32_e32 v2, 1.0, v2
	v_add_f32_e32 v3, 1.0, v3
	v_add_f32_e32 v164, 1.0, v164
	v_add_f32_e32 v165, 1.0, v165
	v_add_f32_e32 v166, 1.0, v166
	v_add_f32_e32 v28, 1.0, v28
	v_rcp_f32_e32 v167, v167
	v_rcp_f32_e32 v1, v1
	v_rcp_f32_e32 v2, v2
	v_rcp_f32_e32 v3, v3
	v_rcp_f32_e32 v164, v164
	v_rcp_f32_e32 v165, v165
	v_rcp_f32_e32 v166, v166
	v_rcp_f32_e32 v28, v28
	v_mul_f32_e32 v15, v15, v167
	v_mul_f32_e32 v1, v16, v1
	v_mul_f32_e32 v2, v17, v2
	v_mul_f32_e32 v3, v18, v3
	v_mul_f32_e32 v16, v19, v164
	v_mul_f32_e32 v17, v12, v165
	v_mul_f32_e32 v18, v13, v166
	v_mul_f32_e32 v19, v14, v28
	v_cvt_pk_bf16_f32 v12, v1, v2
	v_cvt_pk_bf16_f32 v13, v3, v16
	v_cvt_pk_bf16_f32 v14, v17, v18
	v_cvt_pk_bf16_f32 v15, v19, v15
	global_store_dwordx4 v[24:25], v[12:15], off
	s_waitcnt vmcnt(13)
	v_lshlrev_b32_e32 v1, 16, v176
	v_and_b32_e32 v2, 0xffff0000, v176
	v_lshlrev_b32_e32 v3, 16, v177
	v_and_b32_e32 v176, 0xffff0000, v177
	v_lshlrev_b32_e32 v177, 16, v178
	v_and_b32_e32 v178, 0xffff0000, v178
	v_lshlrev_b32_e32 v16, 16, v179
	v_and_b32_e32 v179, 0xffff0000, v179
	v_mul_f32_e32 v2, 0xbfb8aa3b, v2
	v_mul_f32_e32 v3, 0xbfb8aa3b, v3
	v_mul_f32_e32 v177, 0xbfb8aa3b, v177
	v_mul_f32_e32 v178, 0xbfb8aa3b, v178
	v_mul_f32_e32 v1, 0xbfb8aa3b, v1
	v_mul_f32_e32 v176, 0xbfb8aa3b, v176
	v_mul_f32_e32 v16, 0xbfb8aa3b, v16
	v_mul_f32_e32 v179, 0xbfb8aa3b, v179
	v_exp_f32_e32 v2, v2
	v_exp_f32_e32 v3, v3
	v_exp_f32_e32 v177, v177
	v_exp_f32_e32 v178, v178
	v_exp_f32_e32 v1, v1
	v_exp_f32_e32 v176, v176
	v_exp_f32_e32 v16, v16
	v_exp_f32_e32 v179, v179
	v_add_f32_e32 v2, 1.0, v2
	v_add_f32_e32 v3, 1.0, v3
	v_add_f32_e32 v177, 1.0, v177
	v_add_f32_e32 v178, 1.0, v178
	v_add_f32_e32 v1, 1.0, v1
	v_add_f32_e32 v176, 1.0, v176
	v_add_f32_e32 v16, 1.0, v16
	v_add_f32_e32 v179, 1.0, v179
	v_rcp_f32_e32 v2, v2
	v_rcp_f32_e32 v3, v3
	v_rcp_f32_e32 v177, v177
	v_rcp_f32_e32 v178, v178
	v_rcp_f32_e32 v1, v1
	v_rcp_f32_e32 v176, v176
	v_rcp_f32_e32 v16, v16
	v_rcp_f32_e32 v179, v179
	v_mul_f32_e32 v2, v9, v2
	v_mul_f32_e32 v3, v10, v3
	v_mul_f32_e32 v4, v4, v177
	v_mul_f32_e32 v5, v5, v178
	v_mul_f32_e32 v1, v8, v1
	v_mul_f32_e32 v8, v11, v176
	v_mul_f32_e32 v6, v6, v16
	v_mul_f32_e32 v7, v7, v179
	v_cvt_pk_bf16_f32 v2, v1, v2
	v_cvt_pk_bf16_f32 v3, v3, v8
	v_cvt_pk_bf16_f32 v4, v4, v5
	v_cvt_pk_bf16_f32 v5, v6, v7
	global_store_dwordx4 v[24:25], v[2:5], off offset:256
	s_cbranch_vccnz .LBB0_914
	s_andn2_b64 vcc, exec, s[88:89]
	s_cbranch_vccnz .LBB0_913
	s_barrier
	s_branch .LBB0_913
